# combo5 + P2: odd chunks run the memory cross-attention before the spatial-gating groups (memory-bound gating of one half overlaps attention of the other half)
# speedup vs baseline: 1.0048x; 1.0048x over previous
; #define LAS __attribute__((address_space(3)))
; template <bool DO_SGU, bool DO_X>
; __device__ __forceinline__ void mixer_a(const Frame& F, const Args& a) {
;     const f16_t* P = (const f16_t*)(a.ws + WS_P16); f16_t* Y = (f16_t*)(a.ws + WS_Y16);
;     const float* ssv = (const float*)(F.ctl + CW_SSV); const float* gsgu = a.in[6]; const float* wsp = a.in[7]; const float* bsp = a.in[8];
;     LAS float* rv = (LAS float*)(F.lds + XCH_OFF);
;     const int lane = F.lane, fr = lane & 15, G = lane >> 4, qq = fr >> 2, p = fr & 3, w = F.wave;
;     for (int chunk = F.vcu; chunk < M / CHUNK; chunk += F.G) {
;         const int r0 = chunk * CHUNK;
;         if (F.tid < CHUNK) rv[F.tid] = 1.0f / sqrtf(ssv[r0 + F.tid] * (1.0f / MIXW) + EPS);
;         __syncthreads();
.LBB0_320:
	s_cmp_lt_i32 s78, 3
	s_cselect_b64 s[6:7], -1, 0
	s_add_u32 s60, s76, 0x8000000
	s_addc_u32 s61, s77, 0
	s_and_b64 s[0:1], s[6:7], s[0:1]
	s_andn2_b64 vcc, exec, s[0:1]
	s_cbranch_vccnz .LBB0_336
	v_readlane_b32 s0, v238, 2
	s_cmpk_gt_i32 s0, 0xff
	s_cbranch_scc1 .LBB0_336
	s_and_b32 s99, s0, 1
	s_waitcnt vmcnt(4)
	v_and_b32_e32 v2, 16, v0
	v_bfe_u32 v10, v0, 2, 2
	v_cmp_eq_u32_e32 vcc, 0, v2
	v_lshlrev_b32_e32 v2, 3, v0
	v_and_b32_e32 v122, 24, v2
	v_lshlrev_b32_e32 v2, 5, v10
	s_waitcnt lgkmcnt(0)
	v_lshrrev_b32_e32 v83, 4, v206
	v_readlane_b32 s3, v238, 15
	v_xor_b32_e32 v13, 32, v2
	v_xor_b32_e32 v14, 64, v2
	v_xor_b32_e32 v15, 0x60, v2
	v_or_b32_e32 v2, 0x200, v0
	s_lshl_b32 s20, s80, 10
	v_lshlrev_b32_e32 v3, 2, v83
	s_lshr_b32 s37, s3, 7
	v_lshrrev_b32_e32 v124, 4, v2
	v_or_b32_e32 v2, 0x600, v0
	v_add_u32_e32 v4, 12, v3
	s_add_u32 s21, s76, 0x8000600
	v_lshrrev_b32_e32 v123, 4, v0
	v_lshrrev_b32_e32 v126, 4, v2
	v_bfe_u32 v2, v0, 1, 3
	v_and_b32_e32 v1, 15, v0
	v_cndmask_b32_e32 v82, v4, v3, vcc
	s_addc_u32 s22, s77, 0
	s_add_i32 s24, s20, 0x2000
	s_add_i32 s26, s20, 0x4000
	s_add_i32 s28, s20, 0x6000
	v_bitop3_b32 v3, v123, v2, 7 bitop3:0x6c
	v_mov_b32_e32 v81, 0
	s_ashr_i32 s23, s20, 31
	s_ashr_i32 s25, s24, 31
	s_ashr_i32 s27, s26, 31
	s_ashr_i32 s29, s28, 31
	v_lshlrev_b32_e32 v80, 5, v1
	s_add_i32 s2, 0, 0x20000
	v_lshlrev_b32_e32 v130, 5, v3
	v_bitop3_b32 v3, v124, v2, 7 bitop3:0x6c
	v_or_b32_e32 v125, 64, v123
	v_lshl_add_u64 v[84:85], s[16:17], 0, v[80:81]
	v_lshlrev_b32_e32 v133, 5, v3
	v_bitop3_b32 v2, v126, v2, 7 bitop3:0x6c
	s_add_u32 s17, s76, 0x3f00000
	v_lshlrev_b32_e32 v80, 1, v82
	v_lshrrev_b32_e32 v8, 3, v206
	v_lshrrev_b32_e32 v3, 3, v0
	v_lshl_add_u32 v128, v123, 2, s2
	v_lshl_add_u32 v131, v124, 2, s2
	v_lshl_add_u32 v134, v125, 2, s2
	v_lshl_add_u32 v136, v126, 2, s2
	v_lshlrev_b32_e32 v138, 5, v2
	s_addc_u32 s30, s77, 0
	v_lshl_add_u64 v[86:87], s[58:59], 0, v[80:81]
	v_lshl_add_u32 v139, v0, 2, s2
	v_lshlrev_b32_e32 v80, 2, v206
	s_lshl_b32 s2, s80, 5
	v_bitop3_b32 v2, v8, v0, 7 bitop3:0x78
	v_xor_b32_e32 v3, v3, v0
	v_and_b32_e32 v5, 1, v0
	v_lshl_add_u64 v[88:89], s[70:71], 0, v[80:81]
	s_and_b32 s2, s2, 0x60
	v_and_or_b32 v5, v3, 6, v5
	v_lshlrev_b32_e32 v80, 4, v2
	s_lshr_b32 s4, s3, 8
	v_or_b32_e32 v140, s2, v1
	v_lshl_add_u64 v[2:3], s[76:77], 0, v[80:81]
	s_mov_b64 s[2:3], 0x3200000
	v_lshlrev_b32_e32 v80, 4, v5
	v_lshl_add_u64 v[90:91], v[2:3], 0, s[2:3]
	v_lshl_add_u64 v[2:3], s[76:77], 0, v[80:81]
	s_mov_b64 s[2:3], 0x3300000
	v_and_b32_e32 v4, 7, v0
	v_lshl_add_u64 v[92:93], v[2:3], 0, s[2:3]
	v_lshlrev_b32_e32 v2, 7, v1
	v_bitop3_b32 v3, v83, v0, 7 bitop3:0x78
	v_lshl_or_b32 v17, v3, 4, v2
	v_bitop3_b32 v3, v83, v4, 4 bitop3:0x36
	v_readlane_b32 s40, v238, 7
	v_lshl_or_b32 v18, v3, 4, v2
	v_lshlrev_b32_e32 v2, 5, v0
	v_lshlrev_b32_e32 v80, 5, v83
	v_readlane_b32 s41, v238, 8
	v_and_b32_e32 v19, 0x180, v2
	v_bfe_u32 v2, v0, 3, 1
	v_lshl_add_u64 v[94:95], s[40:41], 0, v[80:81]
	v_and_or_b32 v2, v8, 2, v2
	v_lshl_or_b32 v80, s80, 3, v8
	s_add_i32 s3, s80, 8
	v_lshlrev_b32_e32 v141, 5, v2
	v_lshlrev_b64 v[2:3], 6, v[80:81]
	v_lshl_or_b32 v80, s3, 3, v8
	s_lshl_b32 s34, s3, 10
	s_add_i32 s3, s80, 16
	s_lshl_b32 s2, s4, 16
	v_lshlrev_b64 v[4:5], 6, v[80:81]
	v_lshl_or_b32 v80, s3, 3, v8
	s_lshl_b32 s35, s3, 10
	s_add_i32 s3, s80, 24
	v_lshlrev_b32_e32 v11, 11, v83
	v_lshlrev_b32_e32 v12, 8, v10
	v_lshlrev_b32_e32 v16, 4, v0
	v_lshlrev_b64 v[6:7], 6, v[80:81]
	v_lshl_or_b32 v80, s3, 3, v8
	s_add_i32 s2, s2, 0
	v_mul_u32_u24_e32 v10, 0x120, v10
	v_lshlrev_b64 v[8:9], 6, v[80:81]
	v_lshl_add_u32 v23, v83, 9, s2
	v_and_b32_e32 v80, 0xf0, v16
	v_or_b32_e32 v10, v11, v10
	v_lshl_or_b32 v120, s80, 4, v1
	s_movk_i32 s0, 0x80
	v_readlane_b32 s42, v238, 9
	v_xor_b32_e32 v20, 32, v141
	v_xor_b32_e32 v21, 64, v141
	v_xor_b32_e32 v22, 0x60, v141
	v_add3_u32 v142, v23, v19, v122
	v_lshl_add_u64 v[96:97], s[58:59], 0, v[80:81]
	v_and_b32_e32 v80, 48, v206
	v_or3_b32 v15, v15, v11, v12
	v_or3_b32 v14, v14, v11, v12
	v_or3_b32 v12, v13, v11, v12
	v_add_u32_e32 v146, 0, v10
	s_mov_b32 s8, 0x3c003c00
	v_mbcnt_lo_u32_b32 v10, -1, 0
	v_lshlrev_b32_e32 v78, 4, v206
	v_mov_b32_e32 v79, v81
	s_mov_b32 s15, 0
	v_lshlrev_b32_e32 v121, 8, v120
	v_cmp_gt_u32_e64 s[0:1], s0, v0
	v_and_b32_e32 v127, 16, v16
	v_lshlrev_b32_e32 v129, 8, v123
	v_lshlrev_b32_e32 v132, 8, v124
	v_lshlrev_b32_e32 v135, 8, v125
	v_lshlrev_b32_e32 v137, 8, v126
	s_lshl_b32 s31, s4, 6
	s_lshl_b32 s36, s3, 10
	v_lshl_add_u64 v[98:99], s[58:59], 0, v[80:81]
	s_add_i32 s37, s37, 1
	v_add_u32_e32 v143, 0, v15
	v_add_u32_e32 v144, 0, v14
	v_add_u32_e32 v145, 0, v12
	v_mov_b32_e32 v147, 0x358637bd
	s_mov_b32 s38, 0xf800000
	v_mov_b32_e32 v148, 0x260
	s_movk_i32 s39, 0xe00
	s_add_i32 s40, 0, 0x8000
	s_add_i32 s41, 0, 0x18000
	s_mov_b32 s16, 0x3e38aa3b
	v_add_u32_e32 v149, s2, v17
	v_add_u32_e32 v150, s2, v18
	v_add_u32_e32 v151, v142, v20
	v_add_u32_e32 v152, v142, v21
	v_add_u32_e32 v153, v142, v22
	s_mov_b32 s9, s8
	s_mov_b32 s10, s8
	s_mov_b32 s11, s8
	v_mbcnt_hi_u32_b32 v154, -1, v10
	v_lshlrev_b64 v[100:101], 1, v[2:3]
	v_lshlrev_b64 v[102:103], 1, v[4:5]
	v_lshlrev_b64 v[104:105], 1, v[6:7]
	v_lshlrev_b64 v[106:107], 1, v[8:9]
	v_readlane_b32 s42, v238, 2
	v_readlane_b32 s43, v238, 10
	v_readlane_b32 s44, v238, 11
	v_readlane_b32 s45, v238, 12
	v_readlane_b32 s46, v238, 13
	v_readlane_b32 s47, v238, 14
.LBB0_323:
.Lp2_sgu:
	s_lshl_b32 s18, s42, 7
	s_cmp_eq_u32 s99, 1
	s_cbranch_scc1 .Lp2_xattn
	s_and_saveexec_b64 s[4:5], s[0:1]
	s_cbranch_execz .LBB0_325
	v_or_b32_e32 v2, s18, v0
	v_ashrrev_i32_e32 v3, 31, v2
	v_lshl_add_u64 v[2:3], v[2:3], 2, s[12:13]
	global_load_dword v2, v[2:3], off
	s_waitcnt vmcnt(0)
	v_fmamk_f32 v2, v2, 0x3aaaaaab, v147
	v_mul_f32_e32 v3, 0x4f800000, v2
	v_cmp_gt_f32_e32 vcc, s38, v2
	s_nop 1
	v_cndmask_b32_e32 v2, v2, v3, vcc
	v_sqrt_f32_e32 v3, v2
	s_nop 0
	v_add_u32_e32 v4, -1, v3
	v_add_u32_e32 v5, 1, v3
	v_fma_f32 v6, -v4, v3, v2
	v_fma_f32 v7, -v5, v3, v2
	v_cmp_ge_f32_e64 s[2:3], 0, v6
	s_nop 1
	v_cndmask_b32_e64 v3, v3, v4, s[2:3]
	v_cmp_lt_f32_e64 s[2:3], 0, v7
	s_nop 1
	v_cndmask_b32_e64 v3, v3, v5, s[2:3]
	v_mul_f32_e32 v4, 0x37800000, v3
	v_cndmask_b32_e32 v3, v3, v4, vcc
	v_cmp_class_f32_e32 vcc, v2, v148
	s_nop 1
	v_cndmask_b32_e32 v2, v3, v2, vcc
	v_div_scale_f32 v3, s[2:3], v2, v2, 1.0
	v_rcp_f32_e32 v4, v3
	v_div_scale_f32 v5, vcc, 1.0, v2, 1.0
	v_fma_f32 v6, -v3, v4, 1.0
	v_fmac_f32_e32 v4, v6, v4
	v_mul_f32_e32 v6, v5, v4
	v_fma_f32 v7, -v3, v6, v5
	v_fmac_f32_e32 v6, v7, v4
	v_fma_f32 v3, -v3, v6, v5
	v_div_fmas_f32 v3, v3, v4, v6
	v_div_fixup_f32 v2, v3, v2, 1.0
	ds_write_b32 v139, v2

; #define LAS __attribute__((address_space(3)))
; __device__ __forceinline__ unsigned pkh(float lo, float hi) { f32x2 v = {lo, hi}; h16x2 h = __builtin_convertvector(v, h16x2); return __builtin_bit_cast(unsigned, h); }
; __device__ __forceinline__ h16x4 vtr(LAS const unsigned char* p) { return __builtin_bit_cast(h16x4, __builtin_amdgcn_ds_read_tr16_b64_v4i16((LAS v4i16_t*)p)); }
; __device__ __forceinline__ h16x8 cat8(h16x4 lo, h16x4 hi) { return (h16x8){lo[0], lo[1], lo[2], lo[3], hi[0], hi[1], hi[2], hi[3]}; }
; __device__ __forceinline__ int pair16_dim(int G, int dt0) { return (G & 1) ? 16 * (dt0 + 1) + 4 * (G - 1) : 16 * dt0 + 4 * G; }
; template <bool DO_SGU, bool DO_X>
; __device__ __forceinline__ void mixer_a(const Frame& F, const Args& a) {
;     ...
;             for (int ks = 0; ks < nsteps; ++ks) {
;                 const h16x8 bf = *(LAS const h16x8*)(Wimg + (16 * w + fr) * 256 + (((4 * ks + G) ^ fr) << 4));
;                 LAS const unsigned char* v0 = Vimg + (32 * ks + 8 * G + qq) * 256 + p * 8;
; #pragma unroll
;                 for (int dt = 0; dt < 8; ++dt) {
;                     const h16x4 lo = vtr(v0 + ((dt ^ qq) << 5)), hi = vtr(v0 + 4 * 256 + ((dt ^ (4 + qq)) << 5));
;                     acc[dt] = __builtin_amdgcn_mfma_f32_16x16x32_f16(cat8(lo, hi), bf, acc[dt], 0, 0, 0);
;                 }
;             }
;             const float bias = bsp[g * CHUNK + t];
; #pragma unroll
;             for (int pr = 0; pr < 4; ++pr) { const int dt0 = 2 * pr, col = g * 128 + pair16_dim(G, dt0);
;                 u32x2 xa, xb; xa.x = pkh(acc[dt0][0] + bias, acc[dt0][1] + bias); xa.y = pkh(acc[dt0][2] + bias, acc[dt0][3] + bias);
;                 xb.x = pkh(acc[dt0 + 1][0] + bias, acc[dt0 + 1][1] + bias); xb.y = pkh(acc[dt0 + 1][2] + bias, acc[dt0 + 1][3] + bias);
;                 const h16x8 m8 = __builtin_bit_cast(h16x8, pair16(xa, xb));
;                 *(h16x8*)(Y + (size_t)row * DM + col) = ur[pr] * m8; }
.LBB0_331:
	v_xor_b32_e32 v44, v43, v1
	v_add_u32_e32 v48, v41, v122
	v_add_u32_e32 v49, v40, v122
	v_add_u32_e32 v80, v39, v122
	v_lshl_add_u32 v162, v44, 4, v42
	ds_read_b64_tr_b16 v[44:45], v48 offset:32768
	ds_read_b64_tr_b16 v[46:47], v48 offset:33920
	ds_read_b64_tr_b16 v[156:157], v49 offset:32768
	ds_read_b64_tr_b16 v[158:159], v49 offset:33920
	ds_read_b64_tr_b16 v[160:161], v80 offset:32768
	ds_read_b64_tr_b16 v[164:165], v48 offset:32896
	ds_read_b64_tr_b16 v[166:167], v48 offset:33792
	ds_read_b128 v[168:171], v162
	s_waitcnt lgkmcnt(0)
	v_mfma_f32_16x16x32_f16 v[50:53], v[44:47], v[168:171], v[50:53]
	ds_read_b64_tr_b16 v[162:163], v80 offset:33920
	ds_read_b64_tr_b16 v[44:45], v49 offset:32896
	ds_read_b64_tr_b16 v[46:47], v49 offset:33792
	v_add_u32_e32 v155, v38, v122
	s_add_i32 s4, s4, -1
	v_mfma_f32_16x16x32_f16 v[54:57], v[156:159], v[168:171], v[54:57]
	ds_read_b64_tr_b16 v[156:157], v155 offset:32768
	ds_read_b64_tr_b16 v[172:173], v80 offset:32896
	ds_read_b64_tr_b16 v[174:175], v80 offset:33792
	v_add_u32_e32 v38, 0x2000, v38
	v_add_u32_e32 v39, 0x2000, v39
	s_waitcnt lgkmcnt(5)
	v_mfma_f32_16x16x32_f16 v[58:61], v[160:163], v[168:171], v[58:61]
	ds_read_b64_tr_b16 v[158:159], v155 offset:33920
	ds_read_b64_tr_b16 v[160:161], v155 offset:32896
	ds_read_b64_tr_b16 v[162:163], v155 offset:33792
	v_add_u32_e32 v40, 0x2000, v40
	v_add_u32_e32 v41, 0x2000, v41
	s_waitcnt lgkmcnt(2)
	v_mfma_f32_16x16x32_f16 v[62:65], v[156:159], v[168:171], v[62:65]
	s_cmp_eq_u32 s4, 0
	v_add_u32_e32 v43, 4, v43
	v_mfma_f32_16x16x32_f16 v[66:69], v[164:167], v[168:171], v[66:69]
	v_mfma_f32_16x16x32_f16 v[70:73], v[44:47], v[168:171], v[70:73]
	v_mfma_f32_16x16x32_f16 v[74:77], v[172:175], v[168:171], v[74:77]
	s_waitcnt lgkmcnt(0)
	v_mfma_f32_16x16x32_f16 v[34:37], v[160:163], v[168:171], v[34:37]
	s_cbranch_scc0 .LBB0_331
	v_add_u32_e32 v80, s14, v120
	v_lshl_add_u64 v[38:39], v[80:81], 2, s[56:57]
	global_load_dword v156, v[38:39], off
	s_waitcnt vmcnt(4)
	v_mov_b64_e32 v[40:41], v[24:25]
	s_waitcnt vmcnt(3)
	v_mov_b64_e32 v[44:45], v[28:29]
	s_waitcnt vmcnt(2)
	v_mov_b64_e32 v[48:49], v[32:33]
	v_mov_b64_e32 v[38:39], v[22:23]
	v_mov_b64_e32 v[42:43], v[26:27]
	v_mov_b64_e32 v[46:47], v[30:31]
	v_or_b32_e32 v80, s14, v82
	s_xor_b64 s[2:3], s[2:3], -1
	v_lshlrev_b32_e32 v80, 1, v80
	s_cmp_eq_u32 s19, 6
	v_lshl_add_u64 v[22:23], v[116:117], 0, v[80:81]
	s_waitcnt vmcnt(0)
	v_pk_add_f32 v[24:25], v[50:51], v[156:157] op_sel_hi:[1,0]
	v_pk_add_f32 v[26:27], v[52:53], v[156:157] op_sel_hi:[1,0]
	v_pk_add_f32 v[28:29], v[54:55], v[156:157] op_sel_hi:[1,0]
	v_pk_add_f32 v[30:31], v[56:57], v[156:157] op_sel_hi:[1,0]
	v_pk_add_f32 v[52:53], v[62:63], v[156:157] op_sel_hi:[1,0]
	v_pk_add_f32 v[54:55], v[64:65], v[156:157] op_sel_hi:[1,0]
	v_pk_add_f32 v[56:57], v[66:67], v[156:157] op_sel_hi:[1,0]
	v_pk_add_f32 v[64:65], v[74:75], v[156:157] op_sel_hi:[1,0]
	v_pk_add_f32 v[66:67], v[76:77], v[156:157] op_sel_hi:[1,0]
	v_pk_add_f32 v[34:35], v[34:35], v[156:157] op_sel_hi:[1,0]
	v_pk_add_f32 v[36:37], v[36:37], v[156:157] op_sel_hi:[1,0]
	v_cvt_pk_f16_f32 v24, v24, v25
	v_cvt_pk_f16_f32 v25, v26, v27
	v_cvt_pk_f16_f32 v27, v30, v31
	v_cvt_pk_f16_f32 v30, v52, v53
	v_cvt_pk_f16_f32 v52, v64, v65
	v_cvt_pk_f16_f32 v53, v66, v67
	v_cvt_pk_f16_f32 v34, v34, v35
	v_cvt_pk_f16_f32 v35, v36, v37
	v_pk_add_f32 v[32:33], v[58:59], v[156:157] op_sel_hi:[1,0]
	v_pk_add_f32 v[50:51], v[60:61], v[156:157] op_sel_hi:[1,0]
	v_pk_add_f32 v[58:59], v[68:69], v[156:157] op_sel_hi:[1,0]
	v_pk_add_f32 v[60:61], v[70:71], v[156:157] op_sel_hi:[1,0]
	v_pk_add_f32 v[62:63], v[72:73], v[156:157] op_sel_hi:[1,0]
	v_cvt_pk_f16_f32 v26, v28, v29
	v_permlane16_swap_b32_e32 v52, v34
	v_permlane16_swap_b32_e32 v53, v35
	v_cvt_pk_f16_f32 v28, v32, v33
	v_cvt_pk_f16_f32 v29, v50, v51
	v_cvt_pk_f16_f32 v31, v54, v55
	v_cvt_pk_f16_f32 v32, v56, v57
	v_cvt_pk_f16_f32 v33, v58, v59
	v_cvt_pk_f16_f32 v50, v60, v61
	v_cvt_pk_f16_f32 v51, v62, v63
	v_permlane16_swap_b32_e32 v24, v26
	v_permlane16_swap_b32_e32 v25, v27
	v_pk_mul_f16 v5, v5, v35
	v_pk_mul_f16 v4, v4, v34
	v_mov_b64_e32 v[36:37], v[20:21]
	v_permlane16_swap_b32_e32 v28, v30
	v_permlane16_swap_b32_e32 v29, v31
	v_permlane16_swap_b32_e32 v32, v50
	v_permlane16_swap_b32_e32 v33, v51
	v_pk_mul_f16 v17, v17, v27
	v_pk_mul_f16 v15, v15, v25
	v_pk_mul_f16 v16, v16, v26
	v_pk_mul_f16 v14, v14, v24
	v_mov_b64_e32 v[34:35], v[18:19]
	v_pk_mul_f16 v13, v13, v31
	v_pk_mul_f16 v11, v11, v29
	v_pk_mul_f16 v12, v12, v30
	v_pk_mul_f16 v10, v10, v28
	v_pk_mul_f16 v9, v9, v51
	v_pk_mul_f16 v7, v7, v33
	v_pk_mul_f16 v8, v8, v50
	v_pk_mul_f16 v6, v6, v32
	v_pk_mul_f16 v3, v3, v53
	v_pk_mul_f16 v2, v2, v52
	global_store_dwordx4 v[22:23], v[14:17], off
	global_store_dwordx4 v[22:23], v[10:13], off offset:64
	global_store_dwordx4 v[22:23], v[6:9], off offset:128
	global_store_dwordx4 v[22:23], v[2:5], off offset:192
	s_cbranch_scc0 .LBB0_326
	s_cmp_eq_u32 s99, 2
	s_cbranch_scc0 .Lp2_xattn
	s_mov_b32 s99, 1
	s_branch .Lp2_latch
; #define LAS __attribute__((address_space(3)))
; #define VM_WAIT() asm volatile("s_waitcnt vmcnt(0)" ::: "memory")
; __device__ __forceinline__ void dma_kv_imgs(LAS unsigned char* Kimg, LAS unsigned char* Vimg, const f16_t* ksrc, const f16_t* vsrc, int wave, int lane, int pitch = NB) {
;     const int rl = lane >> 3, pos = lane & 7;
;     const int kc = pos ^ rl, vc = 2 * ((pos >> 1) ^ ((lane >> 4) & 3)) + (pos & 1);
;     const unsigned kd = (unsigned)__builtin_amdgcn_readfirstlane((int)(unsigned)(uintptr_t)Kimg), vd = (unsigned)__builtin_amdgcn_readfirstlane((int)(unsigned)(uintptr_t)Vimg);
; #pragma unroll
;     for (int i = 0; i < 4; ++i) { const int pc = wave + 8 * i, row = 8 * pc + rl;
;         glds16_asm(ksrc + (size_t)row * pitch + 8 * kc, (unsigned)__builtin_amdgcn_readfirstlane((int)(kd + pc * 1024)));
;         glds16_asm(vsrc + (size_t)row * pitch + 8 * vc, (unsigned)__builtin_amdgcn_readfirstlane((int)(vd + pc * 1024))); }
; }
; template <bool Y8>
; __device__ __forceinline__ void xattn_chunk(const Frame& F, const Args& a, int chunk, const f16_t* P, int ldp, int qcol0, const float* gqm, f16_t* Y) {
;     const float* gkm = a.in[15];
;     const f16_t* KM = (const f16_t*)(a.ws + WS_KM16); const f16_t* VM = (const f16_t*)(a.ws + WS_VM16);
;     const int r0 = chunk * CHUNK, b = r0 / SEQ, lane = F.lane, fr = lane & 15, G = lane >> 4;
;     const float maxgk = wave_max(fabsf(gkm[lane]));
;     const int hsel = F.wave >> 2, rowa = r0 + 32 * (F.wave & 3) + fr, rowb = rowa + 16;
;     for (int hp = 0; hp < 2; ++hp) {
; #pragma unroll
;         for (int k = 0; k < 2; ++k) dma_kv_imgs(F.lds + k * 65536, F.lds + k * 65536 + 32768, KM + (size_t)(b * 4 + 2 * hp + k) * NMEM * HD, VM + (size_t)(b * 4 + 2 * hp + k) * NMEM * HD, F.wave, lane, HD);
;         const int head = 2 * hp + hsel;
;         h16x8 qa0, qa1, qb0, qb1; float mba, mbb;
;         xattn_load_q(P + (size_t)rowa * ldp + qcol0 + head * HD + 8 * G, gqm, G, maxgk, qa0, qa1, mba);
;         xattn_load_q(P + (size_t)rowb * ldp + qcol0 + head * HD + 8 * G, gqm, G, maxgk, qb0, qb1, mbb);
;         VM_WAIT();
;         __syncthreads();
.Lp2_xattn:
	s_barrier
	global_load_dword v5, v[88:89], off
	v_and_b32_e32 v3, 64, v154
	v_xor_b32_e32 v6, 1, v154
	v_add_u32_e32 v12, 64, v3
	v_cmp_lt_i32_e32 vcc, v6, v12
	v_xor_b32_e32 v7, 2, v154
	v_xor_b32_e32 v8, 4, v154
	v_cndmask_b32_e32 v6, v154, v6, vcc
	v_lshlrev_b32_e32 v6, 2, v6
	v_cmp_lt_i32_e32 vcc, v7, v12
	v_xor_b32_e32 v9, 8, v154
	v_xor_b32_e32 v10, 16, v154
	v_cndmask_b32_e32 v7, v154, v7, vcc
	v_lshlrev_b32_e32 v7, 2, v7
	v_cmp_lt_i32_e32 vcc, v8, v12
	v_xor_b32_e32 v11, 32, v154
	s_ashr_i32 s2, s42, 31
	v_or_b32_e32 v2, s18, v140
	s_lshr_b32 s4, s2, 25
	v_or_b32_e32 v4, 16, v2
	v_ashrrev_i32_e32 v3, 31, v2
	v_mad_i64_i32 v[30:31], s[2:3], v2, s39, v[98:99]
	s_add_i32 s4, s42, s4
	v_mad_i64_i32 v[32:33], s[2:3], v4, s39, v[98:99]
	v_lshlrev_b64 v[34:35], 11, v[2:3]
	s_ashr_i32 s2, s4, 7
	s_mov_b32 s14, 0
	s_lshl_b32 s43, s2, 2
	s_mov_b64 s[18:19], -1
	s_waitcnt vmcnt(0)
	v_and_b32_e32 v13, 0x7fffffff, v5
	ds_bpermute_b32 v6, v6, v13
	v_max_f32_e64 v5, |v5|, |v5|
	s_waitcnt lgkmcnt(0)
	v_max_f32_e32 v6, v6, v6
	v_max_f32_e32 v5, v5, v6
	ds_bpermute_b32 v6, v7, v5
	v_cndmask_b32_e32 v7, v154, v8, vcc
	v_lshlrev_b32_e32 v7, 2, v7
	v_cmp_lt_i32_e32 vcc, v9, v12
	s_waitcnt lgkmcnt(0)
	v_max_f32_e32 v6, v6, v6
	v_max_f32_e32 v5, v5, v6
	ds_bpermute_b32 v6, v7, v5
	v_cndmask_b32_e32 v7, v154, v9, vcc
	v_lshlrev_b32_e32 v7, 2, v7
	v_cmp_lt_i32_e32 vcc, v10, v12
	s_waitcnt lgkmcnt(0)
	v_max_f32_e32 v6, v6, v6
	v_max_f32_e32 v5, v5, v6
	ds_bpermute_b32 v6, v7, v5
	v_cndmask_b32_e32 v7, v154, v10, vcc
	v_lshlrev_b32_e32 v40, 2, v7
	v_cmp_lt_i32_e32 vcc, v11, v12
	s_waitcnt lgkmcnt(0)
	v_max_f32_e32 v6, v6, v6
	v_max_f32_e32 v6, v5, v6
	ds_bpermute_b32 v7, v40, v6
	v_cndmask_b32_e32 v8, v154, v11, vcc
	v_lshlrev_b32_e32 v41, 2, v8
	v_ashrrev_i32_e32 v5, 31, v4
	v_lshlrev_b64 v[36:37], 11, v[4:5]
	s_waitcnt lgkmcnt(0)
	v_max_f32_e32 v7, v7, v7
	v_max_f32_e32 v6, v6, v7
	ds_bpermute_b32 v7, v41, v6
	s_waitcnt lgkmcnt(0)
	v_max_f32_e32 v2, v7, v7
	v_max_f32_e32 v42, v6, v2
.LBB0_334:
	s_lshl_b32 s2, s14, 1
	s_or_b32 s2, s2, s43
	s_ashr_i32 s3, s2, 31
	s_lshl_b64 s[4:5], s[2:3], 15
	v_lshl_add_u64 v[2:3], v[90:91], 0, s[4:5]
	s_add_i32 s3, s20, 0
	v_lshl_add_u64 v[4:5], v[92:93], 0, s[4:5]
	v_lshl_add_u64 v[6:7], v[2:3], 0, v[100:101]
	s_mov_b32 s4, m0
	s_mov_b32 m0, s3
	s_nop 0
	global_load_lds_dwordx4 v[6:7], off
	s_mov_b32 m0, s4
	s_add_i32 s3, s20, s40
	v_lshl_add_u64 v[6:7], v[4:5], 0, v[100:101]
	s_mov_b32 s4, m0
	s_mov_b32 m0, s3
	s_nop 0
	global_load_lds_dwordx4 v[6:7], off
	s_mov_b32 m0, s4
	s_add_i32 s3, s34, 0
	v_lshl_add_u64 v[6:7], v[2:3], 0, v[102:103]
	s_mov_b32 s4, m0
	s_mov_b32 m0, s3
	s_nop 0
	global_load_lds_dwordx4 v[6:7], off
	s_mov_b32 m0, s4
	s_add_i32 s3, s34, s40
	v_lshl_add_u64 v[6:7], v[4:5], 0, v[102:103]
	s_mov_b32 s4, m0
	s_mov_b32 m0, s3
	s_nop 0
	global_load_lds_dwordx4 v[6:7], off
	s_mov_b32 m0, s4
	s_add_i32 s3, s35, 0
	v_lshl_add_u64 v[6:7], v[2:3], 0, v[104:105]
	s_mov_b32 s4, m0
	s_mov_b32 m0, s3
	s_nop 0
	global_load_lds_dwordx4 v[6:7], off
	s_mov_b32 m0, s4
	s_add_i32 s3, s35, s40
	v_lshl_add_u64 v[6:7], v[4:5], 0, v[104:105]
	s_mov_b32 s4, m0
	s_mov_b32 m0, s3
	s_nop 0
	global_load_lds_dwordx4 v[6:7], off
	s_mov_b32 m0, s4
	s_add_i32 s3, s36, 0
	v_lshl_add_u64 v[2:3], v[2:3], 0, v[106:107]
	s_mov_b32 s4, m0
	s_mov_b32 m0, s3
	s_nop 0
	global_load_lds_dwordx4 v[2:3], off
	s_mov_b32 m0, s4
	s_add_i32 s3, s36, s40
	s_or_b32 s2, s2, 1
	v_lshl_add_u64 v[2:3], v[4:5], 0, v[106:107]
	s_mov_b32 s4, m0
	s_mov_b32 m0, s3
	s_nop 0
	global_load_lds_dwordx4 v[2:3], off
	s_mov_b32 m0, s4
	s_ashr_i32 s3, s2, 31
	s_lshl_b64 s[2:3], s[2:3], 15
	v_lshl_add_u64 v[2:3], v[90:91], 0, s[2:3]
	v_lshl_add_u64 v[4:5], v[92:93], 0, s[2:3]
	s_add_i32 s2, 0, 0x10000
	v_lshl_add_u64 v[6:7], v[2:3], 0, v[100:101]
	s_add_i32 s3, s20, s2
	s_mov_b32 s4, m0
	s_mov_b32 m0, s3
	s_nop 0
	global_load_lds_dwordx4 v[6:7], off
	s_mov_b32 m0, s4
	v_lshl_add_u64 v[6:7], v[4:5], 0, v[100:101]
	s_add_i32 s3, s20, s41
	s_mov_b32 s4, m0
	s_mov_b32 m0, s3
	s_nop 0
	global_load_lds_dwordx4 v[6:7], off
	s_mov_b32 m0, s4
	v_lshl_add_u64 v[6:7], v[2:3], 0, v[102:103]
	s_add_i32 s3, s34, s2
	s_mov_b32 s4, m0
	s_mov_b32 m0, s3
	s_nop 0
	global_load_lds_dwordx4 v[6:7], off
	s_mov_b32 m0, s4
	v_lshl_add_u64 v[6:7], v[4:5], 0, v[102:103]
	s_add_i32 s3, s34, s41
	s_mov_b32 s4, m0
	s_mov_b32 m0, s3
	s_nop 0
	global_load_lds_dwordx4 v[6:7], off
	s_mov_b32 m0, s4
	v_lshl_add_u64 v[6:7], v[2:3], 0, v[104:105]
	s_add_i32 s3, s35, s2
	s_mov_b32 s4, m0
	s_mov_b32 m0, s3
	s_nop 0
	global_load_lds_dwordx4 v[6:7], off
	s_mov_b32 m0, s4
	v_lshl_add_u64 v[6:7], v[4:5], 0, v[104:105]
	s_add_i32 s3, s35, s41
	s_mov_b32 s4, m0
	s_mov_b32 m0, s3
	s_nop 0
	global_load_lds_dwordx4 v[6:7], off
	s_mov_b32 m0, s4
	s_add_i32 s2, s36, s2
	v_lshl_add_u64 v[2:3], v[2:3], 0, v[106:107]
	s_mov_b32 s3, m0
	s_mov_b32 m0, s2
	s_nop 0
	global_load_lds_dwordx4 v[2:3], off
	s_mov_b32 m0, s3
	s_add_i32 s2, s36, s41
	v_lshl_add_u64 v[2:3], v[4:5], 0, v[106:107]
	s_mov_b32 s3, m0
	s_mov_b32 m0, s2
	s_nop 0
	global_load_lds_dwordx4 v[2:3], off
	s_mov_b32 m0, s3
	s_lshl_b32 s2, s14, 7
	s_add_i32 s2, s2, s31
	s_lshl_b32 s14, s2, 1
	v_lshl_add_u64 v[10:11], v[30:31], 0, s[14:15]
	global_load_dwordx4 v[2:5], v[10:11], off offset:3136
	v_lshl_add_u64 v[12:13], v[32:33], 0, s[14:15]
	global_load_dwordx4 v[6:9], v[12:13], off offset:3136
	global_load_dwordx4 v[44:47], v[10:11], off offset:3072
	global_load_dwordx4 v[48:51], v[12:13], off offset:3072
	s_nop 0
	global_load_dwordx4 v[10:13], v[94:95], off offset:144
	global_load_dwordx4 v[14:17], v[94:95], off offset:128
	global_load_dwordx4 v[18:21], v[94:95], off offset:16
	global_load_dwordx4 v[22:25], v[94:95], off
	s_waitcnt vmcnt(0)
	s_barrier
; __device__ __forceinline__ unsigned pkh(float lo, float hi) { f32x2 v = {lo, hi}; h16x2 h = __builtin_convertvector(v, h16x2); return __builtin_bit_cast(unsigned, h); }
; __device__ __forceinline__ void xattn_load_q(const f16_t* qp  , const float* gqm, int G, float maxgk, h16x8& q0, h16x8& q1, float& mb) {
;     const h16x8 r0v = *(const h16x8*)qp, r1v = *(const h16x8*)(qp + 32);
;     float q[16], ss = 0.f;
; #pragma unroll
;     for (int j = 0; j < 8; ++j) { q[j] = (float)r0v[j]; q[8 + j] = (float)r1v[j]; ss += q[j] * q[j] + q[8 + j] * q[8 + j]; }
;     ss += __shfl_xor(ss, 16); ss += __shfl_xor(ss, 32);
;     const float rn = 1.0f / sqrtf(ss * (1.0f / HD) + EPS);
;     float n2 = 0.f;
; #pragma unroll
;     for (int j = 0; j < 8; ++j) { q[j] *= rn * gqm[8 * G + j]; q[8 + j] *= rn * gqm[32 + 8 * G + j]; n2 += q[j] * q[j] + q[8 + j] * q[8 + j]; }
;     n2 += __shfl_xor(n2, 16); n2 += __shfl_xor(n2, 32);
;     mb = (sqrtf(n2) * maxgk - BOUND_SHIFT) * LOG2E;
;     const float c = 0.125f * LOG2E;
;     u32x4 w0, w1;
;     w0.x = pkh(q[0] * c, q[1] * c); w0.y = pkh(q[2] * c, q[3] * c); w0.z = pkh(q[4] * c, q[5] * c); w0.w = pkh(q[6] * c, q[7] * c);
;     w1.x = pkh(q[8] * c, q[9] * c); w1.y = pkh(q[10] * c, q[11] * c); w1.z = pkh(q[12] * c, q[13] * c); w1.w = pkh(q[14] * c, q[15] * c);
;     q0 = __builtin_bit_cast(h16x8, w0); q1 = __builtin_bit_cast(h16x8, w1);
; }
	s_waitcnt vmcnt(6)
	v_cvt_f32_f16_e32 v26, v9
	v_cvt_f32_f16_sdwa v27, v9 dst_sel:DWORD dst_unused:UNUSED_PAD src0_sel:WORD_1
	v_cvt_f32_f16_e32 v28, v8
	v_cvt_f32_f16_sdwa v29, v8 dst_sel:DWORD dst_unused:UNUSED_PAD src0_sel:WORD_1
	v_cvt_f32_f16_e32 v56, v2
	v_cvt_f32_f16_sdwa v57, v2 dst_sel:DWORD dst_unused:UNUSED_PAD src0_sel:WORD_1
	v_cvt_f32_f16_e32 v8, v3
	v_cvt_f32_f16_sdwa v9, v3 dst_sel:DWORD dst_unused:UNUSED_PAD src0_sel:WORD_1
	s_waitcnt vmcnt(5)
	v_cvt_f32_f16_e32 v64, v44
	v_cvt_f32_f16_sdwa v65, v44 dst_sel:DWORD dst_unused:UNUSED_PAD src0_sel:WORD_1
	v_cvt_f32_f16_e32 v60, v47
	v_cvt_f32_f16_sdwa v61, v47 dst_sel:DWORD dst_unused:UNUSED_PAD src0_sel:WORD_1
	v_cvt_f32_f16_e32 v62, v46
	v_cvt_f32_f16_sdwa v63, v46 dst_sel:DWORD dst_unused:UNUSED_PAD src0_sel:WORD_1
	v_cvt_f32_f16_e32 v46, v45
	v_cvt_f32_f16_sdwa v47, v45 dst_sel:DWORD dst_unused:UNUSED_PAD src0_sel:WORD_1
	v_cvt_f32_f16_e32 v54, v4
	v_cvt_f32_f16_sdwa v55, v4 dst_sel:DWORD dst_unused:UNUSED_PAD src0_sel:WORD_1
	v_pk_mul_f32 v[2:3], v[56:57], v[56:57]
	v_cvt_f32_f16_e32 v52, v5
	v_cvt_f32_f16_sdwa v53, v5 dst_sel:DWORD dst_unused:UNUSED_PAD src0_sel:WORD_1
	v_pk_mul_f32 v[66:67], v[8:9], v[8:9]
	v_pk_fma_f32 v[2:3], v[64:65], v[64:65], v[2:3]
	v_pk_fma_f32 v[66:67], v[46:47], v[46:47], v[66:67]
	v_add_f32_e32 v2, v2, v3
	v_pk_mul_f32 v[44:45], v[54:55], v[54:55]
	v_add_f32_e32 v2, v66, v2
	v_pk_fma_f32 v[44:45], v[62:63], v[62:63], v[44:45]
	v_add_f32_e32 v2, v67, v2
	v_pk_mul_f32 v[4:5], v[52:53], v[52:53]
	v_add_f32_e32 v2, v44, v2
	v_pk_fma_f32 v[4:5], v[60:61], v[60:61], v[4:5]
	v_add_f32_e32 v2, v45, v2
	v_add_f32_e32 v2, v4, v2
	v_add_f32_e32 v2, v5, v2
	ds_bpermute_b32 v3, v40, v2
	s_waitcnt vmcnt(4)
	v_cvt_f32_f16_e32 v44, v51
	v_cvt_f32_f16_sdwa v45, v51 dst_sel:DWORD dst_unused:UNUSED_PAD src0_sel:WORD_1
	v_cvt_f32_f16_e32 v66, v50
	v_cvt_f32_f16_sdwa v67, v50 dst_sel:DWORD dst_unused:UNUSED_PAD src0_sel:WORD_1
	s_waitcnt lgkmcnt(0)
	v_add_f32_e32 v2, v2, v3
	ds_bpermute_b32 v3, v41, v2
	v_cvt_f32_f16_e32 v50, v49
	v_cvt_f32_f16_sdwa v51, v49 dst_sel:DWORD dst_unused:UNUSED_PAD src0_sel:WORD_1
	v_cvt_f32_f16_e32 v38, v7
	v_cvt_f32_f16_sdwa v39, v7 dst_sel:DWORD dst_unused:UNUSED_PAD src0_sel:WORD_1
	s_waitcnt lgkmcnt(0)
	v_add_f32_e32 v2, v2, v3
	v_fmamk_f32 v2, v2, 0x3c800000, v147
	v_mul_f32_e32 v3, 0x4f800000, v2
	v_cmp_gt_f32_e32 vcc, s38, v2
	v_pk_mul_f32 v[4:5], v[28:29], v[28:29]
	v_cvt_f32_f16_e32 v58, v6
	v_cndmask_b32_e32 v43, v2, v3, vcc
	v_sqrt_f32_e32 v49, v43
	v_pk_mul_f32 v[2:3], v[26:27], v[26:27]
	v_cvt_f32_f16_sdwa v59, v6 dst_sel:DWORD dst_unused:UNUSED_PAD src0_sel:WORD_1
	v_pk_fma_f32 v[68:69], v[44:45], v[44:45], v[2:3]
	v_add_u32_e32 v2, -1, v49
	v_add_u32_e32 v3, 1, v49
	v_fma_f32 v70, -v2, v49, v43
	v_fma_f32 v71, -v3, v49, v43
	v_cmp_ge_f32_e64 s[2:3], 0, v70
	v_pk_mul_f32 v[6:7], v[58:59], v[58:59]
	s_nop 0
	v_cndmask_b32_e64 v2, v49, v2, s[2:3]
	v_cmp_lt_f32_e64 s[2:3], 0, v71
	v_pk_fma_f32 v[70:71], v[66:67], v[66:67], v[4:5]
	s_nop 0
	v_cndmask_b32_e64 v2, v2, v3, s[2:3]
	v_mul_f32_e32 v3, 0x37800000, v2
	v_cndmask_b32_e32 v2, v2, v3, vcc
	v_cmp_class_f32_e32 vcc, v43, v148
	s_nop 1
	v_cndmask_b32_e32 v43, v2, v43, vcc
	v_div_scale_f32 v49, s[2:3], v43, v43, 1.0
	v_rcp_f32_e32 v74, v49
	v_pk_mul_f32 v[2:3], v[38:39], v[38:39]
	s_nop 0
	v_pk_fma_f32 v[72:73], v[50:51], v[50:51], v[2:3]
	v_fma_f32 v2, -v49, v74, 1.0
	v_fmac_f32_e32 v74, v2, v74
	v_div_scale_f32 v2, vcc, 1.0, v43, 1.0
	v_mul_f32_e32 v3, v2, v74
	v_fma_f32 v4, -v49, v3, v2
	v_fmac_f32_e32 v3, v4, v74
	v_fma_f32 v2, -v49, v3, v2
	v_div_fmas_f32 v2, v2, v74, v3
	v_div_fixup_f32 v74, v2, v43, 1.0
	s_waitcnt vmcnt(3)
	v_pk_mul_f32 v[2:3], v[12:13], v[74:75] op_sel_hi:[1,0]
	s_nop 0
	v_pk_mul_f32 v[52:53], v[2:3], v[52:53]
	s_nop 0
	v_pk_mul_f32 v[2:3], v[52:53], s[16:17] op_sel_hi:[1,0]
	s_nop 0
	v_cvt_pk_f16_f32 v5, v2, v3
	v_pk_mul_f32 v[2:3], v[10:11], v[74:75] op_sel_hi:[1,0]
	s_nop 0
	v_pk_mul_f32 v[54:55], v[2:3], v[54:55]
	s_nop 0
	v_pk_mul_f32 v[2:3], v[54:55], s[16:17] op_sel_hi:[1,0]
	s_nop 0
	v_cvt_pk_f16_f32 v4, v2, v3
	s_waitcnt vmcnt(2)
	v_pk_mul_f32 v[2:3], v[16:17], v[74:75] op_sel_hi:[1,0]
	s_nop 0
	v_pk_mul_f32 v[76:77], v[2:3], v[8:9]
	v_pk_mul_f32 v[8:9], v[14:15], v[74:75] op_sel_hi:[1,0]
	v_pk_mul_f32 v[2:3], v[76:77], s[16:17] op_sel_hi:[1,0]
	v_pk_mul_f32 v[56:57], v[8:9], v[56:57]
	v_cvt_pk_f16_f32 v3, v2, v3
	v_pk_mul_f32 v[8:9], v[56:57], s[16:17] op_sel_hi:[1,0]
	s_nop 0
	v_cvt_pk_f16_f32 v2, v8, v9
	s_waitcnt vmcnt(1)
	v_pk_mul_f32 v[8:9], v[20:21], v[74:75] op_sel_hi:[1,0]
	s_nop 0
	v_pk_mul_f32 v[60:61], v[8:9], v[60:61]
	s_nop 0
	v_pk_mul_f32 v[8:9], v[60:61], s[16:17] op_sel_hi:[1,0]
	v_pk_mul_f32 v[60:61], v[60:61], v[60:61]
	v_cvt_pk_f16_f32 v9, v8, v9
	v_pk_fma_f32 v[52:53], v[52:53], v[52:53], v[60:61]
	v_pk_mul_f32 v[60:61], v[18:19], v[74:75] op_sel_hi:[1,0]
	s_nop 0
	v_pk_mul_f32 v[60:61], v[60:61], v[62:63]
	s_nop 0
	v_pk_mul_f32 v[62:63], v[60:61], v[60:61]
	s_nop 0
	v_pk_fma_f32 v[54:55], v[54:55], v[54:55], v[62:63]
	s_waitcnt vmcnt(0)
	v_pk_mul_f32 v[62:63], v[24:25], v[74:75] op_sel_hi:[1,0]
	v_pk_mul_f32 v[74:75], v[22:23], v[74:75] op_sel_hi:[1,0]
	v_pk_mul_f32 v[46:47], v[62:63], v[46:47]
	s_nop 0
	v_pk_mul_f32 v[62:63], v[46:47], v[46:47]
	s_nop 0
	v_pk_fma_f32 v[62:63], v[76:77], v[76:77], v[62:63]
	v_cvt_f32_f16_e32 v76, v48
	v_cvt_f32_f16_sdwa v77, v48 dst_sel:DWORD dst_unused:UNUSED_PAD src0_sel:WORD_1
	v_pk_mul_f32 v[48:49], v[74:75], v[64:65]
	v_pk_fma_f32 v[6:7], v[76:77], v[76:77], v[6:7]
	v_pk_mul_f32 v[64:65], v[48:49], v[48:49]
	v_add_f32_e32 v6, v6, v7
	v_pk_fma_f32 v[56:57], v[56:57], v[56:57], v[64:65]
	v_add_f32_e32 v6, v72, v6
	v_add_f32_e32 v8, v56, v57
	v_add_f32_e32 v8, v62, v8
	v_add_f32_e32 v8, v63, v8
	v_add_f32_e32 v6, v73, v6
	v_add_f32_e32 v8, v54, v8
	v_add_f32_e32 v6, v70, v6
	v_add_f32_e32 v8, v55, v8
	v_add_f32_e32 v6, v71, v6
	v_add_f32_e32 v8, v52, v8
	v_add_f32_e32 v6, v68, v6
	v_add_f32_e32 v43, v53, v8
	v_add_f32_e32 v53, v69, v6
	ds_bpermute_b32 v54, v40, v53
	ds_bpermute_b32 v52, v40, v43
	v_pk_mul_f32 v[6:7], v[60:61], s[16:17] op_sel_hi:[1,0]
	s_waitcnt lgkmcnt(1)
; template <bool CAUSAL, bool SHARED> ...
;     const int fr = lane & 15, G = lane >> 4, qq = fr >> 2, p = fr & 3;
;     const int kof0 = fr * 128 + (((0 + G) ^ (fr & 7)) << 4), kof1 = fr * 128 + (((4 + G) ^ (fr & 7)) << 4);
;     const int vrow = (4 * G + qq) * 128 + p * 8, sw = (2 * G + (qq >> 1)) & 3;
;     const h16x8 ones = {(_Float16)1.0f, (_Float16)1.0f, (_Float16)1.0f, (_Float16)1.0f, (_Float16)1.0f, (_Float16)1.0f, (_Float16)1.0f, (_Float16)1.0f};
;     const f32x4 nma = {-mba, -mba, -mba, -mba}, nmb = {-mbb, -mbb, -mbb, -mbb};
;     f32x4 la = {0.f, 0.f, 0.f, 0.f}, lb = la;
;     h16x8 ka[4], kb[4];
;     ka[0] = *(LAS const h16x8*)(Ka + kof0); ka[1] = *(LAS const h16x8*)(Ka + kof1); ka[2] = *(LAS const h16x8*)(Ka + 2048 + kof0); ka[3] = *(LAS const h16x8*)(Ka + 2048 + kof1);
;     if (!SHARED) { kb[0] = *(LAS const h16x8*)(Kb + kof0); kb[1] = *(LAS const h16x8*)(Kb + kof1); kb[2] = *(LAS const h16x8*)(Kb + 2048 + kof0); kb[3] = *(LAS const h16x8*)(Kb + 2048 + kof1); }
;     for (int ks = 0; ks < nsteps; ++ks) {
;         LAS const unsigned char* va = Va + ks * 4096 + vrow; LAS const unsigned char* vb = Vb + ks * 4096 + vrow;
; __device__ __forceinline__ void xattn_load_q(const f16_t* qp  , const float* gqm, int G, float maxgk, h16x8& q0, h16x8& q1, float& mb) {
;     const h16x8 r0v = *(const h16x8*)qp, r1v = *(const h16x8*)(qp + 32);
;     float q[16], ss = 0.f;
; #pragma unroll
;     for (int j = 0; j < 8; ++j) { q[j] = (float)r0v[j]; q[8 + j] = (float)r1v[j]; ss += q[j] * q[j] + q[8 + j] * q[8 + j]; }
;     ss += __shfl_xor(ss, 16); ss += __shfl_xor(ss, 32);
;     const float rn = 1.0f / sqrtf(ss * (1.0f / HD) + EPS);
;     float n2 = 0.f;
; #pragma unroll
;     for (int j = 0; j < 8; ++j) { q[j] *= rn * gqm[8 * G + j]; q[8 + j] *= rn * gqm[32 + 8 * G + j]; n2 += q[j] * q[j] + q[8 + j] * q[8 + j]; }
;     n2 += __shfl_xor(n2, 16); n2 += __shfl_xor(n2, 32);
;     mb = (sqrtf(n2) * maxgk - BOUND_SHIFT) * LOG2E;
;     const float c = 0.125f * LOG2E;
;     u32x4 w0, w1;
;     w0.x = pkh(q[0] * c, q[1] * c); w0.y = pkh(q[2] * c, q[3] * c); w0.z = pkh(q[4] * c, q[5] * c); w0.w = pkh(q[6] * c, q[7] * c);
;     w1.x = pkh(q[8] * c, q[9] * c); w1.y = pkh(q[10] * c, q[11] * c); w1.z = pkh(q[12] * c, q[13] * c); w1.w = pkh(q[14] * c, q[15] * c);
;     q0 = __builtin_bit_cast(h16x8, w0); q1 = __builtin_bit_cast(h16x8, w1);
; }
	v_add_f32_e32 v53, v53, v54
	ds_bpermute_b32 v54, v41, v53
	v_cvt_pk_f16_f32 v8, v6, v7
	s_waitcnt lgkmcnt(1)
	v_add_f32_e32 v43, v43, v52
	v_pk_mul_f32 v[6:7], v[46:47], s[16:17] op_sel_hi:[1,0]
	ds_bpermute_b32 v52, v41, v43
	s_waitcnt lgkmcnt(1)
	v_add_f32_e32 v46, v53, v54
	v_fmamk_f32 v46, v46, 0x3c800000, v147
	v_mul_f32_e32 v47, 0x4f800000, v46
	v_cmp_gt_f32_e32 vcc, s38, v46
	v_cvt_pk_f16_f32 v7, v6, v7
	s_waitcnt lgkmcnt(0)
	v_add_f32_e32 v6, v43, v52
	v_cndmask_b32_e32 v46, v46, v47, vcc
	v_sqrt_f32_e32 v47, v46
	v_mul_f32_e32 v43, 0x4f800000, v6
	v_cmp_gt_f32_e64 s[2:3], s38, v6
	s_nop 1
	v_cndmask_b32_e64 v43, v6, v43, s[2:3]
	v_add_u32_e32 v6, -1, v47
	v_fma_f32 v52, -v6, v47, v46
	v_cmp_ge_f32_e64 s[4:5], 0, v52
	v_add_u32_e32 v52, 1, v47
	v_sqrt_f32_e32 v54, v43
	v_cndmask_b32_e64 v6, v47, v6, s[4:5]
	v_fma_f32 v47, -v52, v47, v46
	v_cmp_lt_f32_e64 s[4:5], 0, v47
	s_nop 1
	v_cndmask_b32_e64 v6, v6, v52, s[4:5]
	v_mul_f32_e32 v47, 0x37800000, v6
	v_cndmask_b32_e32 v6, v6, v47, vcc
	v_cmp_class_f32_e32 vcc, v46, v148
	s_nop 1
	v_cndmask_b32_e32 v52, v6, v46, vcc
	v_div_scale_f32 v53, s[4:5], v52, v52, 1.0
	v_rcp_f32_e32 v55, v53
	v_pk_mul_f32 v[46:47], v[48:49], s[16:17] op_sel_hi:[1,0]
	s_nop 0
	v_cvt_pk_f16_f32 v6, v46, v47
	v_fma_f32 v46, -v53, v55, 1.0
	v_fmac_f32_e32 v55, v46, v55
	v_div_scale_f32 v46, vcc, 1.0, v52, 1.0
	v_mul_f32_e32 v48, v46, v55
	v_fma_f32 v49, -v53, v48, v46
	v_fmac_f32_e32 v48, v49, v55
	v_fma_f32 v46, -v53, v48, v46
	v_div_fmas_f32 v46, v46, v55, v48
	v_add_u32_e32 v47, -1, v54
	v_div_fixup_f32 v46, v46, v52, 1.0
	v_pk_mul_f32 v[22:23], v[22:23], v[46:47] op_sel_hi:[1,0]
	v_pk_mul_f32 v[14:15], v[14:15], v[46:47] op_sel_hi:[1,0]
	v_pk_mul_f32 v[22:23], v[22:23], v[76:77]
	v_pk_mul_f32 v[24:25], v[24:25], v[46:47] op_sel_hi:[1,0]
	v_pk_mul_f32 v[48:49], v[22:23], v[22:23]
	v_pk_mul_f32 v[52:53], v[14:15], v[58:59]
	v_pk_mul_f32 v[24:25], v[24:25], v[50:51]
	v_pk_mul_f32 v[16:17], v[16:17], v[46:47] op_sel_hi:[1,0]
	v_pk_fma_f32 v[14:15], v[52:53], v[52:53], v[48:49]
	v_pk_mul_f32 v[38:39], v[16:17], v[38:39]
	v_pk_mul_f32 v[16:17], v[24:25], v[24:25]
	v_pk_mul_f32 v[18:19], v[18:19], v[46:47] op_sel_hi:[1,0]
	v_pk_fma_f32 v[16:17], v[38:39], v[38:39], v[16:17]
	v_pk_mul_f32 v[18:19], v[18:19], v[66:67]
	v_pk_mul_f32 v[10:11], v[10:11], v[46:47] op_sel_hi:[1,0]
	v_add_f32_e32 v14, v14, v15
	v_pk_mul_f32 v[10:11], v[10:11], v[28:29]
	v_pk_mul_f32 v[28:29], v[18:19], v[18:19]
	v_pk_mul_f32 v[20:21], v[20:21], v[46:47] op_sel_hi:[1,0]
	v_add_f32_e32 v14, v16, v14
	v_pk_fma_f32 v[28:29], v[10:11], v[10:11], v[28:29]
	v_pk_mul_f32 v[20:21], v[20:21], v[44:45]
	v_pk_mul_f32 v[12:13], v[12:13], v[46:47] op_sel_hi:[1,0]
	v_add_f32_e32 v14, v17, v14
	v_pk_mul_f32 v[12:13], v[12:13], v[26:27]
	v_pk_mul_f32 v[26:27], v[20:21], v[20:21]
	v_add_f32_e32 v14, v28, v14
	v_pk_fma_f32 v[26:27], v[12:13], v[12:13], v[26:27]
	v_add_f32_e32 v14, v29, v14
	v_add_f32_e32 v14, v26, v14
	v_add_f32_e32 v14, v27, v14
	ds_bpermute_b32 v15, v40, v14
	v_fma_f32 v16, -v47, v54, v43
	v_add_u32_e32 v17, 1, v54
	v_cmp_ge_f32_e32 vcc, 0, v16
	v_fma_f32 v26, -v17, v54, v43
	s_waitcnt lgkmcnt(0)
	v_add_f32_e32 v14, v14, v15
	ds_bpermute_b32 v15, v41, v14
	v_cndmask_b32_e32 v16, v54, v47, vcc
	v_cmp_lt_f32_e32 vcc, 0, v26
	v_pk_mul_f32 v[10:11], v[10:11], s[16:17] op_sel_hi:[1,0]
	s_waitcnt lgkmcnt(0)
	v_add_f32_e32 v14, v14, v15
	v_cndmask_b32_e32 v16, v16, v17, vcc
	v_mul_f32_e32 v15, 0x4f800000, v14
	v_cmp_gt_f32_e32 vcc, s38, v14
	v_mul_f32_e32 v17, 0x37800000, v16
	v_cndmask_b32_e64 v16, v16, v17, s[2:3]
	v_cndmask_b32_e32 v14, v14, v15, vcc
	v_sqrt_f32_e32 v15, v14
	v_cmp_class_f32_e64 s[2:3], v43, v148
	s_nop 1
	v_cndmask_b32_e64 v26, v16, v43, s[2:3]
	v_add_u32_e32 v16, -1, v15
	v_fma_f32 v17, -v16, v15, v14
	v_cmp_ge_f32_e64 s[2:3], 0, v17
	v_add_u32_e32 v17, 1, v15
	s_nop 0
	v_cndmask_b32_e64 v16, v15, v16, s[2:3]
	v_fma_f32 v15, -v17, v15, v14
	v_cmp_lt_f32_e64 s[2:3], 0, v15
	s_nop 1
	v_cndmask_b32_e64 v15, v16, v17, s[2:3]
	v_mul_f32_e32 v16, 0x37800000, v15
	v_cndmask_b32_e32 v15, v15, v16, vcc
	v_cmp_class_f32_e32 vcc, v14, v148
	v_pk_mul_f32 v[16:17], v[24:25], s[16:17] op_sel_hi:[1,0]
	s_nop 0
	v_cndmask_b32_e32 v27, v15, v14, vcc
	v_pk_mul_f32 v[14:15], v[22:23], s[16:17] op_sel_hi:[1,0]
	s_nop 0
	v_cvt_pk_f16_f32 v14, v14, v15
	v_cvt_pk_f16_f32 v15, v16, v17
	v_pk_mul_f32 v[16:17], v[18:19], s[16:17] op_sel_hi:[1,0]
	v_pk_mul_f32 v[18:19], v[20:21], s[16:17] op_sel_hi:[1,0]
	v_cvt_pk_f16_f32 v16, v16, v17
	v_cvt_pk_f16_f32 v17, v18, v19
	v_pk_mul_f32 v[18:19], v[52:53], s[16:17] op_sel_hi:[1,0]
	v_pk_mul_f32 v[20:21], v[38:39], s[16:17] op_sel_hi:[1,0]
	v_cvt_pk_f16_f32 v18, v18, v19
	v_cvt_pk_f16_f32 v19, v20, v21
	v_cvt_pk_f16_f32 v20, v10, v11
	v_pk_mul_f32 v[10:11], v[12:13], s[16:17] op_sel_hi:[1,0]
	v_add_u32_e32 v38, v142, v141
	v_cvt_pk_f16_f32 v21, v10, v11
	v_fma_f32 v10, v42, v26, -4.0
	v_mul_f32_e32 v22, 0xbfb8aa3b, v10
	ds_read_b128 v[10:13], v149
	ds_read_b128 v[44:47], v149 offset:2048
	ds_read_b128 v[48:51], v150
	ds_read_b128 v[52:55], v150 offset:2048
	ds_read_b64_tr_b16 v[56:57], v38 offset:32768
	ds_read_b64_tr_b16 v[58:59], v38 offset:34816
	ds_read_b64_tr_b16 v[60:61], v151 offset:32768
	ds_read_b64_tr_b16 v[62:63], v151 offset:34816
	ds_read_b64_tr_b16 v[64:65], v152 offset:32768
	ds_read_b64_tr_b16 v[66:67], v152 offset:34816
	ds_read_b64_tr_b16 v[68:69], v153 offset:32768
	ds_read_b64_tr_b16 v[70:71], v153 offset:34816
	v_fma_f32 v26, v42, v27, -4.0
	v_mul_f32_e32 v26, 0xbfb8aa3b, v26
	v_mov_b32_e32 v23, v22
	v_mov_b32_e32 v24, v22
	v_mov_b32_e32 v25, v22
	v_mov_b32_e32 v27, v26
	v_mov_b32_e32 v28, v26
	v_mov_b32_e32 v29, v26
	s_waitcnt lgkmcnt(11)
; #define LAS __attribute__((address_space(3)))
; template <bool CAUSAL, bool SHARED> ...
;     ...
;     for (int ks = 0; ks < nsteps; ++ks) {
;         LAS const unsigned char* va = Va + ks * 4096 + vrow; LAS const unsigned char* vb = Vb + ks * 4096 + vrow;
;         h16x4 fal[4], fah[4], fbl[4], fbh[4];
; #pragma unroll
;         for (int dt = 0; dt < 4; ++dt) { fal[dt] = vtr(va + ((dt ^ sw) << 5)); fah[dt] = vtr(va + 2048 + ((dt ^ sw) << 5));
;             if (!SHARED) { fbl[dt] = vtr(vb + ((dt ^ sw) << 5)); fbh[dt] = vtr(vb + 2048 + ((dt ^ sw) << 5)); } }
;         __builtin_amdgcn_sched_barrier(0);
;         f32x4 sa0, sa1, sb0, sb1;
;         sa0 = __builtin_amdgcn_mfma_f32_16x16x32_f16(ka[0], qa0, nma, 0, 0, 0); sb0 = __builtin_amdgcn_mfma_f32_16x16x32_f16(SHARED ? ka[0] : kb[0], qb0, nmb, 0, 0, 0);
;         sa1 = __builtin_amdgcn_mfma_f32_16x16x32_f16(ka[2], qa0, nma, 0, 0, 0); sb1 = __builtin_amdgcn_mfma_f32_16x16x32_f16(SHARED ? ka[2] : kb[2], qb0, nmb, 0, 0, 0);
;         sa0 = __builtin_amdgcn_mfma_f32_16x16x32_f16(ka[1], qa1, sa0, 0, 0, 0); sb0 = __builtin_amdgcn_mfma_f32_16x16x32_f16(SHARED ? ka[1] : kb[1], qb1, sb0, 0, 0, 0);
;         sa1 = __builtin_amdgcn_mfma_f32_16x16x32_f16(ka[3], qa1, sa1, 0, 0, 0); sb1 = __builtin_amdgcn_mfma_f32_16x16x32_f16(SHARED ? ka[3] : kb[3], qb1, sb1, 0, 0, 0);
;         __builtin_amdgcn_sched_barrier(0);
;         if (ks + 1 < nsteps) { LAS const unsigned char* kn = Ka + (ks + 1) * 4096;
;             ka[0] = *(LAS const h16x8*)(kn + kof0); ka[1] = *(LAS const h16x8*)(kn + kof1); ka[2] = *(LAS const h16x8*)(kn + 2048 + kof0); ka[3] = *(LAS const h16x8*)(kn + 2048 + kof1);
;             if (!SHARED) { LAS const unsigned char* kn2 = Kb + (ks + 1) * 4096;
;                 kb[0] = *(LAS const h16x8*)(kn2 + kof0); kb[1] = *(LAS const h16x8*)(kn2 + kof1); kb[2] = *(LAS const h16x8*)(kn2 + 2048 + kof0); kb[3] = *(LAS const h16x8*)(kn2 + 2048 + kof1); } }
;         __builtin_amdgcn_sched_barrier(0);
;         f32x4 pa0, pa1, pb0, pb1;
; #pragma unroll
;         for (int e = 0; e < 4; ++e) { pa0[e] = __builtin_amdgcn_exp2f(sa0[e]); pa1[e] = __builtin_amdgcn_exp2f(sa1[e]);
;                                       pb0[e] = __builtin_amdgcn_exp2f(sb0[e]); pb1[e] = __builtin_amdgcn_exp2f(sb1[e]); }
;         if (CAUSAL) { const int kr = ks * 32 + 4 * G;
; #pragma unroll
	v_mfma_f32_16x16x32_f16 v[72:75], v[10:13], v[6:9], v[22:25]
	v_mfma_f32_16x16x32_f16 v[10:13], v[10:13], v[14:17], v[26:29]
	s_waitcnt lgkmcnt(10)
	v_mfma_f32_16x16x32_f16 v[108:111], v[44:47], v[6:9], v[22:25]
	v_mfma_f32_16x16x32_f16 v[44:47], v[44:47], v[14:17], v[26:29]
	s_waitcnt lgkmcnt(9)
	v_mfma_f32_16x16x32_f16 v[72:75], v[48:51], v[2:5], v[72:75]
	v_mfma_f32_16x16x32_f16 v[48:51], v[48:51], v[18:21], v[10:13]
	s_waitcnt lgkmcnt(8)
	v_mfma_f32_16x16x32_f16 v[10:13], v[52:55], v[2:5], v[108:111]
	v_mfma_f32_16x16x32_f16 v[44:47], v[52:55], v[18:21], v[44:47]
	ds_read_b128 v[52:55], v150 offset:6144
	s_nop 0
	ds_read_b128 v[108:111], v150 offset:4096
	ds_read_b128 v[112:115], v149 offset:6144
	ds_read_b128 v[116:119], v149 offset:4096
	ds_read_b64_tr_b16 v[168:169], v38 offset:36864
	ds_read_b64_tr_b16 v[170:171], v38 offset:38912
	ds_read_b64_tr_b16 v[172:173], v151 offset:36864
	ds_read_b64_tr_b16 v[174:175], v151 offset:38912
	ds_read_b64_tr_b16 v[176:177], v152 offset:36864
	ds_read_b64_tr_b16 v[178:179], v152 offset:38912
	ds_read_b64_tr_b16 v[180:181], v153 offset:36864
	ds_read_b64_tr_b16 v[182:183], v153 offset:38912
	v_exp_f32_e32 v39, v72
	v_exp_f32_e32 v43, v10
	v_exp_f32_e32 v76, v44
	v_exp_f32_e32 v44, v73
	v_exp_f32_e32 v77, v11
	v_exp_f32_e32 v155, v12
	v_exp_f32_e32 v160, v50
	v_exp_f32_e32 v50, v13
	v_mov_b64_e32 v[12:13], s[10:11]
	v_exp_f32_e32 v48, v48
	v_exp_f32_e32 v49, v49
	v_exp_f32_e32 v80, v45
	v_exp_f32_e32 v45, v74
	v_exp_f32_e32 v161, v46
	v_exp_f32_e32 v46, v75
	v_mov_b64_e32 v[10:11], s[8:9]
	v_cvt_pk_f16_f32 v72, v39, v44
	v_cvt_pk_f16_f32 v74, v43, v77
	v_exp_f32_e32 v39, v51
	v_exp_f32_e32 v43, v47
	v_cvt_pk_f16_f32 v73, v45, v46
	v_cvt_pk_f16_f32 v75, v155, v50
	v_cvt_pk_f16_f32 v44, v48, v49
	v_cvt_pk_f16_f32 v45, v160, v39
	v_cvt_pk_f16_f32 v46, v76, v80
	v_cvt_pk_f16_f32 v47, v161, v43
	v_mfma_f32_16x16x32_f16 v[156:159], v[10:13], v[72:75], 0
	s_waitcnt lgkmcnt(14)
	v_mfma_f32_16x16x32_f16 v[48:51], v[56:59], v[72:75], 0
	v_mfma_f32_16x16x32_f16 v[56:59], v[56:59], v[44:47], 0
	v_mfma_f32_16x16x32_f16 v[160:163], v[60:63], v[72:75], 0
	v_mfma_f32_16x16x32_f16 v[60:63], v[60:63], v[44:47], 0
	v_mfma_f32_16x16x32_f16 v[164:167], v[64:67], v[72:75], 0
	v_mfma_f32_16x16x32_f16 v[64:67], v[64:67], v[44:47], 0
	s_waitcnt lgkmcnt(12)
	v_mfma_f32_16x16x32_f16 v[72:75], v[68:71], v[72:75], 0
	v_mfma_f32_16x16x32_f16 v[68:71], v[68:71], v[44:47], 0
	v_mfma_f32_16x16x32_f16 v[44:47], v[10:13], v[44:47], 0
	s_waitcnt lgkmcnt(8)
	v_mfma_f32_16x16x32_f16 v[184:187], v[116:119], v[6:9], v[22:25]
	v_mfma_f32_16x16x32_f16 v[116:119], v[116:119], v[14:17], v[26:29]
	v_mfma_f32_16x16x32_f16 v[188:191], v[112:115], v[6:9], v[22:25]
	v_mfma_f32_16x16x32_f16 v[112:115], v[112:115], v[14:17], v[26:29]
	v_mfma_f32_16x16x32_f16 v[184:187], v[108:111], v[2:5], v[184:187]
	v_mfma_f32_16x16x32_f16 v[108:111], v[108:111], v[18:21], v[116:119]
	v_mfma_f32_16x16x32_f16 v[116:119], v[52:55], v[2:5], v[188:191]
	v_mfma_f32_16x16x32_f16 v[52:55], v[52:55], v[18:21], v[112:115]
	s_nop 3
	ds_read_b128 v[112:115], v150 offset:10240
	ds_read_b128 v[188:191], v150 offset:8192
	ds_read_b128 v[192:195], v149 offset:10240
	ds_read_b128 v[196:199], v149 offset:8192
	v_exp_f32_e32 v39, v184
	v_exp_f32_e32 v43, v116
	v_exp_f32_e32 v77, v52
	v_exp_f32_e32 v52, v185
	v_exp_f32_e32 v80, v117
	v_exp_f32_e32 v76, v108
	v_exp_f32_e32 v108, v109
	v_exp_f32_e32 v109, v53
	v_exp_f32_e32 v53, v186
	v_exp_f32_e32 v155, v118
	v_exp_f32_e32 v110, v110
	v_exp_f32_e32 v117, v187
	v_exp_f32_e32 v184, v54
	v_exp_f32_e32 v54, v119
	v_cvt_pk_f16_f32 v116, v39, v52
	v_cvt_pk_f16_f32 v118, v43, v80
	v_exp_f32_e32 v39, v111
	v_exp_f32_e32 v43, v55
	v_cvt_pk_f16_f32 v117, v53, v117
	v_cvt_pk_f16_f32 v119, v155, v54
	v_cvt_pk_f16_f32 v52, v76, v108
	v_cvt_pk_f16_f32 v53, v110, v39
	v_cvt_pk_f16_f32 v54, v77, v109
	v_cvt_pk_f16_f32 v55, v184, v43
	v_mfma_f32_16x16x32_f16 v[156:159], v[10:13], v[116:119], v[156:159]
	s_waitcnt lgkmcnt(10)
	v_mfma_f32_16x16x32_f16 v[48:51], v[168:171], v[116:119], v[48:51]
	v_mfma_f32_16x16x32_f16 v[56:59], v[168:171], v[52:55], v[56:59]
	s_waitcnt lgkmcnt(8)
	v_mfma_f32_16x16x32_f16 v[108:111], v[172:175], v[116:119], v[160:163]
	v_mfma_f32_16x16x32_f16 v[60:63], v[172:175], v[52:55], v[60:63]
	s_waitcnt lgkmcnt(6)
	v_mfma_f32_16x16x32_f16 v[160:163], v[176:179], v[116:119], v[164:167]
	s_waitcnt lgkmcnt(4)
	v_mfma_f32_16x16x32_f16 v[72:75], v[180:183], v[116:119], v[72:75]
	ds_read_b64_tr_b16 v[116:117], v38 offset:40960
	ds_read_b64_tr_b16 v[118:119], v38 offset:43008
	ds_read_b64_tr_b16 v[164:165], v151 offset:40960
	ds_read_b64_tr_b16 v[166:167], v151 offset:43008
	ds_read_b64_tr_b16 v[168:169], v152 offset:40960
	ds_read_b64_tr_b16 v[170:171], v152 offset:43008
	ds_read_b64_tr_b16 v[172:173], v153 offset:40960
	ds_read_b64_tr_b16 v[174:175], v153 offset:43008
	v_mfma_f32_16x16x32_f16 v[64:67], v[176:179], v[52:55], v[64:67]
	v_mfma_f32_16x16x32_f16 v[68:71], v[180:183], v[52:55], v[68:71]
	v_mfma_f32_16x16x32_f16 v[44:47], v[10:13], v[52:55], v[44:47]
	s_waitcnt lgkmcnt(8)
; #define LAS __attribute__((address_space(3)))
; template <bool CAUSAL, bool SHARED> ...
;     ...
;     for (int ks = 0; ks < nsteps; ++ks) {
;         LAS const unsigned char* va = Va + ks * 4096 + vrow; LAS const unsigned char* vb = Vb + ks * 4096 + vrow;
;         h16x4 fal[4], fah[4], fbl[4], fbh[4];
; #pragma unroll
;         for (int dt = 0; dt < 4; ++dt) { fal[dt] = vtr(va + ((dt ^ sw) << 5)); fah[dt] = vtr(va + 2048 + ((dt ^ sw) << 5));
;             if (!SHARED) { fbl[dt] = vtr(vb + ((dt ^ sw) << 5)); fbh[dt] = vtr(vb + 2048 + ((dt ^ sw) << 5)); } }
;         __builtin_amdgcn_sched_barrier(0);
;         f32x4 sa0, sa1, sb0, sb1;
;         sa0 = __builtin_amdgcn_mfma_f32_16x16x32_f16(ka[0], qa0, nma, 0, 0, 0); sb0 = __builtin_amdgcn_mfma_f32_16x16x32_f16(SHARED ? ka[0] : kb[0], qb0, nmb, 0, 0, 0);
;         sa1 = __builtin_amdgcn_mfma_f32_16x16x32_f16(ka[2], qa0, nma, 0, 0, 0); sb1 = __builtin_amdgcn_mfma_f32_16x16x32_f16(SHARED ? ka[2] : kb[2], qb0, nmb, 0, 0, 0);
;         sa0 = __builtin_amdgcn_mfma_f32_16x16x32_f16(ka[1], qa1, sa0, 0, 0, 0); sb0 = __builtin_amdgcn_mfma_f32_16x16x32_f16(SHARED ? ka[1] : kb[1], qb1, sb0, 0, 0, 0);
;         sa1 = __builtin_amdgcn_mfma_f32_16x16x32_f16(ka[3], qa1, sa1, 0, 0, 0); sb1 = __builtin_amdgcn_mfma_f32_16x16x32_f16(SHARED ? ka[3] : kb[3], qb1, sb1, 0, 0, 0);
;         __builtin_amdgcn_sched_barrier(0);
;         if (ks + 1 < nsteps) { LAS const unsigned char* kn = Ka + (ks + 1) * 4096;
;             ka[0] = *(LAS const h16x8*)(kn + kof0); ka[1] = *(LAS const h16x8*)(kn + kof1); ka[2] = *(LAS const h16x8*)(kn + 2048 + kof0); ka[3] = *(LAS const h16x8*)(kn + 2048 + kof1);
;             if (!SHARED) { LAS const unsigned char* kn2 = Kb + (ks + 1) * 4096;
;                 kb[0] = *(LAS const h16x8*)(kn2 + kof0); kb[1] = *(LAS const h16x8*)(kn2 + kof1); kb[2] = *(LAS const h16x8*)(kn2 + 2048 + kof0); kb[3] = *(LAS const h16x8*)(kn2 + 2048 + kof1); } }
;         __builtin_amdgcn_sched_barrier(0);
;         f32x4 pa0, pa1, pb0, pb1;
; #pragma unroll
;         for (int e = 0; e < 4; ++e) { pa0[e] = __builtin_amdgcn_exp2f(sa0[e]); pa1[e] = __builtin_amdgcn_exp2f(sa1[e]);
;                                       pb0[e] = __builtin_amdgcn_exp2f(sb0[e]); pb1[e] = __builtin_amdgcn_exp2f(sb1[e]); }
;         if (CAUSAL) { const int kr = ks * 32 + 4 * G;
; #pragma unroll
	v_mfma_f32_16x16x32_f16 v[52:55], v[196:199], v[6:9], v[22:25]
	v_mfma_f32_16x16x32_f16 v[176:179], v[196:199], v[14:17], v[26:29]
	v_mfma_f32_16x16x32_f16 v[180:183], v[192:195], v[6:9], v[22:25]
	v_mfma_f32_16x16x32_f16 v[184:187], v[192:195], v[14:17], v[26:29]
	v_mfma_f32_16x16x32_f16 v[52:55], v[188:191], v[2:5], v[52:55]
	v_mfma_f32_16x16x32_f16 v[176:179], v[188:191], v[18:21], v[176:179]
	v_mfma_f32_16x16x32_f16 v[180:183], v[112:115], v[2:5], v[180:183]
	v_mfma_f32_16x16x32_f16 v[112:115], v[112:115], v[18:21], v[184:187]
	s_nop 3
	ds_read_b128 v[184:187], v150 offset:14336
	ds_read_b128 v[188:191], v150 offset:12288
	ds_read_b128 v[192:195], v149 offset:14336
	ds_read_b128 v[196:199], v149 offset:12288
	v_exp_f32_e32 v39, v52
	v_exp_f32_e32 v43, v180
	v_exp_f32_e32 v52, v53
	v_exp_f32_e32 v80, v181
	v_exp_f32_e32 v53, v54
	v_exp_f32_e32 v54, v55
	v_exp_f32_e32 v76, v176
	v_exp_f32_e32 v77, v112
	v_exp_f32_e32 v112, v177
	v_exp_f32_e32 v155, v113
	v_exp_f32_e32 v113, v182
	v_exp_f32_e32 v176, v178
	v_exp_f32_e32 v177, v114
	v_exp_f32_e32 v55, v183
	v_cvt_pk_f16_f32 v52, v39, v52
	v_cvt_pk_f16_f32 v53, v53, v54
	v_cvt_pk_f16_f32 v54, v43, v80
	v_exp_f32_e32 v39, v179
	v_exp_f32_e32 v43, v115
	v_cvt_pk_f16_f32 v55, v113, v55
	v_cvt_pk_f16_f32 v112, v76, v112
	v_cvt_pk_f16_f32 v113, v176, v39
	v_cvt_pk_f16_f32 v114, v77, v155
	v_cvt_pk_f16_f32 v115, v177, v43
	v_mfma_f32_16x16x32_f16 v[156:159], v[10:13], v[52:55], v[156:159]
	s_waitcnt lgkmcnt(10)
	v_mfma_f32_16x16x32_f16 v[48:51], v[116:119], v[52:55], v[48:51]
	v_mfma_f32_16x16x32_f16 v[56:59], v[116:119], v[112:115], v[56:59]
	s_waitcnt lgkmcnt(8)
	v_mfma_f32_16x16x32_f16 v[108:111], v[164:167], v[52:55], v[108:111]
	v_mfma_f32_16x16x32_f16 v[60:63], v[164:167], v[112:115], v[60:63]
	s_waitcnt lgkmcnt(6)
	v_mfma_f32_16x16x32_f16 v[116:119], v[168:171], v[52:55], v[160:163]
	v_mfma_f32_16x16x32_f16 v[64:67], v[168:171], v[112:115], v[64:67]
	s_waitcnt lgkmcnt(4)
	v_mfma_f32_16x16x32_f16 v[52:55], v[172:175], v[52:55], v[72:75]
	s_nop 2
	ds_read_b64_tr_b16 v[72:73], v38 offset:45056
	ds_read_b64_tr_b16 v[74:75], v38 offset:47104
	ds_read_b64_tr_b16 v[160:161], v151 offset:45056
	ds_read_b64_tr_b16 v[162:163], v151 offset:47104
	ds_read_b64_tr_b16 v[164:165], v152 offset:45056
	ds_read_b64_tr_b16 v[166:167], v152 offset:47104
	ds_read_b64_tr_b16 v[168:169], v153 offset:45056
	ds_read_b64_tr_b16 v[170:171], v153 offset:47104
	v_mfma_f32_16x16x32_f16 v[68:71], v[172:175], v[112:115], v[68:71]
	v_mfma_f32_16x16x32_f16 v[44:47], v[10:13], v[112:115], v[44:47]
	s_waitcnt lgkmcnt(8)
	v_mfma_f32_16x16x32_f16 v[112:115], v[196:199], v[6:9], v[22:25]
	v_mfma_f32_16x16x32_f16 v[172:175], v[196:199], v[14:17], v[26:29]
	v_mfma_f32_16x16x32_f16 v[176:179], v[192:195], v[6:9], v[22:25]
	v_mfma_f32_16x16x32_f16 v[180:183], v[192:195], v[14:17], v[26:29]
	v_mfma_f32_16x16x32_f16 v[112:115], v[188:191], v[2:5], v[112:115]
	v_mfma_f32_16x16x32_f16 v[172:175], v[188:191], v[18:21], v[172:175]
	v_mfma_f32_16x16x32_f16 v[176:179], v[184:187], v[2:5], v[176:179]
	v_mfma_f32_16x16x32_f16 v[180:183], v[184:187], v[18:21], v[180:183]
	ds_read_b128 v[184:187], v150 offset:18432
	ds_read_b128 v[188:191], v150 offset:16384
	ds_read_b128 v[192:195], v149 offset:18432
	ds_read_b128 v[196:199], v149 offset:16384
	s_nop 0
	v_exp_f32_e32 v39, v112
	s_nop 0
	v_exp_f32_e32 v43, v176
	v_exp_f32_e32 v80, v113
	v_exp_f32_e32 v155, v177
	v_exp_f32_e32 v113, v114
	v_exp_f32_e32 v114, v115
	v_exp_f32_e32 v76, v172
	v_exp_f32_e32 v77, v180
	v_exp_f32_e32 v172, v173
	v_exp_f32_e32 v176, v181
	v_exp_f32_e32 v173, v178
	v_exp_f32_e32 v174, v174
	v_exp_f32_e32 v177, v182
	v_exp_f32_e32 v115, v179
	v_cvt_pk_f16_f32 v112, v39, v80
	v_cvt_pk_f16_f32 v113, v113, v114
	v_cvt_pk_f16_f32 v114, v43, v155
	v_exp_f32_e32 v39, v175
	v_exp_f32_e32 v43, v183
	v_cvt_pk_f16_f32 v115, v173, v115
	v_cvt_pk_f16_f32 v172, v76, v172
	v_cvt_pk_f16_f32 v173, v174, v39
	v_cvt_pk_f16_f32 v174, v77, v176
	v_cvt_pk_f16_f32 v175, v177, v43
	v_mfma_f32_16x16x32_f16 v[156:159], v[10:13], v[112:115], v[156:159]
	s_waitcnt lgkmcnt(10)
	v_mfma_f32_16x16x32_f16 v[48:51], v[72:75], v[112:115], v[48:51]
	v_mfma_f32_16x16x32_f16 v[56:59], v[72:75], v[172:175], v[56:59]
	s_waitcnt lgkmcnt(8)
	v_mfma_f32_16x16x32_f16 v[72:75], v[160:163], v[112:115], v[108:111]
	v_mfma_f32_16x16x32_f16 v[60:63], v[160:163], v[172:175], v[60:63]
	s_waitcnt lgkmcnt(6)
	v_mfma_f32_16x16x32_f16 v[108:111], v[164:167], v[112:115], v[116:119]
	v_mfma_f32_16x16x32_f16 v[64:67], v[164:167], v[172:175], v[64:67]
	s_waitcnt lgkmcnt(4)
	v_mfma_f32_16x16x32_f16 v[52:55], v[168:171], v[112:115], v[52:55]
	ds_read_b64_tr_b16 v[112:113], v38 offset:49152
	ds_read_b64_tr_b16 v[114:115], v38 offset:51200
	ds_read_b64_tr_b16 v[116:117], v151 offset:49152
	ds_read_b64_tr_b16 v[118:119], v151 offset:51200
	ds_read_b64_tr_b16 v[160:161], v152 offset:49152
	ds_read_b64_tr_b16 v[162:163], v152 offset:51200
	ds_read_b64_tr_b16 v[164:165], v153 offset:49152
	ds_read_b64_tr_b16 v[166:167], v153 offset:51200
	v_mfma_f32_16x16x32_f16 v[68:71], v[168:171], v[172:175], v[68:71]
	v_mfma_f32_16x16x32_f16 v[44:47], v[10:13], v[172:175], v[44:47]
	s_waitcnt lgkmcnt(8)
; #define LAS __attribute__((address_space(3)))
; template <bool CAUSAL, bool SHARED> ...
;     ...
;     for (int ks = 0; ks < nsteps; ++ks) {
;         LAS const unsigned char* va = Va + ks * 4096 + vrow; LAS const unsigned char* vb = Vb + ks * 4096 + vrow;
;         h16x4 fal[4], fah[4], fbl[4], fbh[4];
; #pragma unroll
;         for (int dt = 0; dt < 4; ++dt) { fal[dt] = vtr(va + ((dt ^ sw) << 5)); fah[dt] = vtr(va + 2048 + ((dt ^ sw) << 5));
;             if (!SHARED) { fbl[dt] = vtr(vb + ((dt ^ sw) << 5)); fbh[dt] = vtr(vb + 2048 + ((dt ^ sw) << 5)); } }
;         __builtin_amdgcn_sched_barrier(0);
;         f32x4 sa0, sa1, sb0, sb1;
;         sa0 = __builtin_amdgcn_mfma_f32_16x16x32_f16(ka[0], qa0, nma, 0, 0, 0); sb0 = __builtin_amdgcn_mfma_f32_16x16x32_f16(SHARED ? ka[0] : kb[0], qb0, nmb, 0, 0, 0);
;         sa1 = __builtin_amdgcn_mfma_f32_16x16x32_f16(ka[2], qa0, nma, 0, 0, 0); sb1 = __builtin_amdgcn_mfma_f32_16x16x32_f16(SHARED ? ka[2] : kb[2], qb0, nmb, 0, 0, 0);
;         sa0 = __builtin_amdgcn_mfma_f32_16x16x32_f16(ka[1], qa1, sa0, 0, 0, 0); sb0 = __builtin_amdgcn_mfma_f32_16x16x32_f16(SHARED ? ka[1] : kb[1], qb1, sb0, 0, 0, 0);
;         sa1 = __builtin_amdgcn_mfma_f32_16x16x32_f16(ka[3], qa1, sa1, 0, 0, 0); sb1 = __builtin_amdgcn_mfma_f32_16x16x32_f16(SHARED ? ka[3] : kb[3], qb1, sb1, 0, 0, 0);
;         __builtin_amdgcn_sched_barrier(0);
;         if (ks + 1 < nsteps) { LAS const unsigned char* kn = Ka + (ks + 1) * 4096;
;             ka[0] = *(LAS const h16x8*)(kn + kof0); ka[1] = *(LAS const h16x8*)(kn + kof1); ka[2] = *(LAS const h16x8*)(kn + 2048 + kof0); ka[3] = *(LAS const h16x8*)(kn + 2048 + kof1);
;             if (!SHARED) { LAS const unsigned char* kn2 = Kb + (ks + 1) * 4096;
;                 kb[0] = *(LAS const h16x8*)(kn2 + kof0); kb[1] = *(LAS const h16x8*)(kn2 + kof1); kb[2] = *(LAS const h16x8*)(kn2 + 2048 + kof0); kb[3] = *(LAS const h16x8*)(kn2 + 2048 + kof1); } }
;         __builtin_amdgcn_sched_barrier(0);
;         f32x4 pa0, pa1, pb0, pb1;
; #pragma unroll
;         for (int e = 0; e < 4; ++e) { pa0[e] = __builtin_amdgcn_exp2f(sa0[e]); pa1[e] = __builtin_amdgcn_exp2f(sa1[e]);
;                                       pb0[e] = __builtin_amdgcn_exp2f(sb0[e]); pb1[e] = __builtin_amdgcn_exp2f(sb1[e]); }
;         if (CAUSAL) { const int kr = ks * 32 + 4 * G;
; #pragma unroll
	v_mfma_f32_16x16x32_f16 v[168:171], v[196:199], v[6:9], v[22:25]
	v_mfma_f32_16x16x32_f16 v[172:175], v[196:199], v[14:17], v[26:29]
	v_mfma_f32_16x16x32_f16 v[176:179], v[192:195], v[6:9], v[22:25]
	v_mfma_f32_16x16x32_f16 v[180:183], v[192:195], v[14:17], v[26:29]
	v_mfma_f32_16x16x32_f16 v[168:171], v[188:191], v[2:5], v[168:171]
	v_mfma_f32_16x16x32_f16 v[172:175], v[188:191], v[18:21], v[172:175]
	v_mfma_f32_16x16x32_f16 v[176:179], v[184:187], v[2:5], v[176:179]
	v_mfma_f32_16x16x32_f16 v[180:183], v[184:187], v[18:21], v[180:183]
	ds_read_b128 v[184:187], v150 offset:22528
	ds_read_b128 v[188:191], v150 offset:20480
	ds_read_b128 v[192:195], v149 offset:22528
	ds_read_b128 v[196:199], v149 offset:20480
	s_nop 0
	v_exp_f32_e32 v39, v168
	s_nop 0
	v_exp_f32_e32 v43, v176
	v_exp_f32_e32 v80, v169
	v_exp_f32_e32 v155, v177
	v_exp_f32_e32 v169, v170
	v_exp_f32_e32 v170, v171
	v_exp_f32_e32 v76, v172
	v_exp_f32_e32 v77, v180
	v_exp_f32_e32 v172, v173
	v_exp_f32_e32 v176, v181
	v_exp_f32_e32 v173, v178
	v_exp_f32_e32 v174, v174
	v_exp_f32_e32 v177, v182
	v_exp_f32_e32 v171, v179
	v_cvt_pk_f16_f32 v168, v39, v80
	v_cvt_pk_f16_f32 v169, v169, v170
	v_cvt_pk_f16_f32 v170, v43, v155
	v_exp_f32_e32 v39, v175
	v_exp_f32_e32 v43, v183
	v_cvt_pk_f16_f32 v171, v173, v171
	v_cvt_pk_f16_f32 v172, v76, v172
	v_cvt_pk_f16_f32 v173, v174, v39
	v_cvt_pk_f16_f32 v174, v77, v176
	v_cvt_pk_f16_f32 v175, v177, v43
	s_waitcnt lgkmcnt(10)
	v_mfma_f32_16x16x32_f16 v[48:51], v[112:115], v[168:171], v[48:51]
	v_mfma_f32_16x16x32_f16 v[56:59], v[112:115], v[172:175], v[56:59]
	s_waitcnt lgkmcnt(8)
	v_mfma_f32_16x16x32_f16 v[72:75], v[116:119], v[168:171], v[72:75]
	v_mfma_f32_16x16x32_f16 v[60:63], v[116:119], v[172:175], v[60:63]
	s_waitcnt lgkmcnt(6)
	v_mfma_f32_16x16x32_f16 v[108:111], v[160:163], v[168:171], v[108:111]
	v_mfma_f32_16x16x32_f16 v[64:67], v[160:163], v[172:175], v[64:67]
	s_waitcnt lgkmcnt(4)
	v_mfma_f32_16x16x32_f16 v[52:55], v[164:167], v[168:171], v[52:55]
	v_mfma_f32_16x16x32_f16 v[68:71], v[164:167], v[172:175], v[68:71]
	ds_read_b64_tr_b16 v[112:113], v38 offset:53248
	ds_read_b64_tr_b16 v[114:115], v38 offset:55296
	ds_read_b64_tr_b16 v[116:117], v151 offset:53248
	ds_read_b64_tr_b16 v[118:119], v151 offset:55296
	ds_read_b64_tr_b16 v[160:161], v152 offset:53248
	ds_read_b64_tr_b16 v[162:163], v152 offset:55296
	ds_read_b64_tr_b16 v[164:165], v153 offset:53248
	ds_read_b64_tr_b16 v[166:167], v153 offset:55296
	v_mfma_f32_16x16x32_f16 v[156:159], v[10:13], v[168:171], v[156:159]
	v_mfma_f32_16x16x32_f16 v[44:47], v[10:13], v[172:175], v[44:47]
	s_waitcnt lgkmcnt(8)
	v_mfma_f32_16x16x32_f16 v[168:171], v[196:199], v[6:9], v[22:25]
	v_mfma_f32_16x16x32_f16 v[172:175], v[196:199], v[14:17], v[26:29]
	v_mfma_f32_16x16x32_f16 v[176:179], v[192:195], v[6:9], v[22:25]
	v_mfma_f32_16x16x32_f16 v[180:183], v[192:195], v[14:17], v[26:29]
	v_mfma_f32_16x16x32_f16 v[168:171], v[188:191], v[2:5], v[168:171]
	v_mfma_f32_16x16x32_f16 v[172:175], v[188:191], v[18:21], v[172:175]
	v_mfma_f32_16x16x32_f16 v[176:179], v[184:187], v[2:5], v[176:179]
	v_mfma_f32_16x16x32_f16 v[180:183], v[184:187], v[18:21], v[180:183]
	ds_read_b128 v[184:187], v150 offset:26624
	ds_read_b128 v[188:191], v150 offset:24576
	ds_read_b128 v[192:195], v149 offset:26624
	ds_read_b128 v[196:199], v149 offset:24576
	s_nop 0
	v_exp_f32_e32 v39, v168
	s_nop 0
	v_exp_f32_e32 v43, v176
	v_exp_f32_e32 v80, v169
	v_exp_f32_e32 v155, v177
	v_exp_f32_e32 v169, v170
	v_exp_f32_e32 v170, v171
	v_exp_f32_e32 v76, v172
	v_exp_f32_e32 v77, v180
	v_exp_f32_e32 v172, v173
	v_exp_f32_e32 v176, v181
	v_exp_f32_e32 v173, v178
	v_exp_f32_e32 v174, v174
	v_exp_f32_e32 v177, v182
	v_exp_f32_e32 v171, v179
	v_cvt_pk_f16_f32 v168, v39, v80
	v_cvt_pk_f16_f32 v169, v169, v170
	v_cvt_pk_f16_f32 v170, v43, v155
	v_exp_f32_e32 v39, v175
	v_exp_f32_e32 v43, v183
	v_cvt_pk_f16_f32 v171, v173, v171
	v_cvt_pk_f16_f32 v172, v76, v172
	v_cvt_pk_f16_f32 v173, v174, v39
	v_cvt_pk_f16_f32 v174, v77, v176
	v_cvt_pk_f16_f32 v175, v177, v43
	s_waitcnt lgkmcnt(10)
	v_mfma_f32_16x16x32_f16 v[48:51], v[112:115], v[168:171], v[48:51]
	v_mfma_f32_16x16x32_f16 v[56:59], v[112:115], v[172:175], v[56:59]
	s_waitcnt lgkmcnt(8)
	v_mfma_f32_16x16x32_f16 v[72:75], v[116:119], v[168:171], v[72:75]
	v_mfma_f32_16x16x32_f16 v[60:63], v[116:119], v[172:175], v[60:63]
	s_waitcnt lgkmcnt(6)
	v_mfma_f32_16x16x32_f16 v[108:111], v[160:163], v[168:171], v[108:111]
	v_mfma_f32_16x16x32_f16 v[64:67], v[160:163], v[172:175], v[64:67]
	s_waitcnt lgkmcnt(4)
	v_mfma_f32_16x16x32_f16 v[52:55], v[164:167], v[168:171], v[52:55]
	v_mfma_f32_16x16x32_f16 v[68:71], v[164:167], v[172:175], v[68:71]
	ds_read_b64_tr_b16 v[112:113], v38 offset:57344
	ds_read_b64_tr_b16 v[114:115], v38 offset:59392
	ds_read_b64_tr_b16 v[116:117], v151 offset:57344
	ds_read_b64_tr_b16 v[118:119], v151 offset:59392
	ds_read_b64_tr_b16 v[160:161], v152 offset:57344
	ds_read_b64_tr_b16 v[162:163], v152 offset:59392
	ds_read_b64_tr_b16 v[164:165], v153 offset:57344
	ds_read_b64_tr_b16 v[166:167], v153 offset:59392
	v_mfma_f32_16x16x32_f16 v[156:159], v[10:13], v[168:171], v[156:159]
	v_mfma_f32_16x16x32_f16 v[44:47], v[10:13], v[172:175], v[44:47]
	s_waitcnt lgkmcnt(8)
; #define LAS __attribute__((address_space(3)))
; template <bool CAUSAL, bool SHARED> ...
;     ...
;     for (int ks = 0; ks < nsteps; ++ks) {
;         LAS const unsigned char* va = Va + ks * 4096 + vrow; LAS const unsigned char* vb = Vb + ks * 4096 + vrow;
;         h16x4 fal[4], fah[4], fbl[4], fbh[4];
; #pragma unroll
;         for (int dt = 0; dt < 4; ++dt) { fal[dt] = vtr(va + ((dt ^ sw) << 5)); fah[dt] = vtr(va + 2048 + ((dt ^ sw) << 5));
;             if (!SHARED) { fbl[dt] = vtr(vb + ((dt ^ sw) << 5)); fbh[dt] = vtr(vb + 2048 + ((dt ^ sw) << 5)); } }
;         __builtin_amdgcn_sched_barrier(0);
;         f32x4 sa0, sa1, sb0, sb1;
;         sa0 = __builtin_amdgcn_mfma_f32_16x16x32_f16(ka[0], qa0, nma, 0, 0, 0); sb0 = __builtin_amdgcn_mfma_f32_16x16x32_f16(SHARED ? ka[0] : kb[0], qb0, nmb, 0, 0, 0);
;         sa1 = __builtin_amdgcn_mfma_f32_16x16x32_f16(ka[2], qa0, nma, 0, 0, 0); sb1 = __builtin_amdgcn_mfma_f32_16x16x32_f16(SHARED ? ka[2] : kb[2], qb0, nmb, 0, 0, 0);
;         sa0 = __builtin_amdgcn_mfma_f32_16x16x32_f16(ka[1], qa1, sa0, 0, 0, 0); sb0 = __builtin_amdgcn_mfma_f32_16x16x32_f16(SHARED ? ka[1] : kb[1], qb1, sb0, 0, 0, 0);
;         sa1 = __builtin_amdgcn_mfma_f32_16x16x32_f16(ka[3], qa1, sa1, 0, 0, 0); sb1 = __builtin_amdgcn_mfma_f32_16x16x32_f16(SHARED ? ka[3] : kb[3], qb1, sb1, 0, 0, 0);
;         __builtin_amdgcn_sched_barrier(0);
;         if (ks + 1 < nsteps) { LAS const unsigned char* kn = Ka + (ks + 1) * 4096;
;             ka[0] = *(LAS const h16x8*)(kn + kof0); ka[1] = *(LAS const h16x8*)(kn + kof1); ka[2] = *(LAS const h16x8*)(kn + 2048 + kof0); ka[3] = *(LAS const h16x8*)(kn + 2048 + kof1);
;             if (!SHARED) { LAS const unsigned char* kn2 = Kb + (ks + 1) * 4096;
;                 kb[0] = *(LAS const h16x8*)(kn2 + kof0); kb[1] = *(LAS const h16x8*)(kn2 + kof1); kb[2] = *(LAS const h16x8*)(kn2 + 2048 + kof0); kb[3] = *(LAS const h16x8*)(kn2 + 2048 + kof1); } }
;         __builtin_amdgcn_sched_barrier(0);
;         f32x4 pa0, pa1, pb0, pb1;
; #pragma unroll
;         for (int e = 0; e < 4; ++e) { pa0[e] = __builtin_amdgcn_exp2f(sa0[e]); pa1[e] = __builtin_amdgcn_exp2f(sa1[e]);
;                                       pb0[e] = __builtin_amdgcn_exp2f(sb0[e]); pb1[e] = __builtin_amdgcn_exp2f(sb1[e]); }
;         if (CAUSAL) { const int kr = ks * 32 + 4 * G;
; #pragma unroll
	v_mfma_f32_16x16x32_f16 v[168:171], v[196:199], v[6:9], v[22:25]
	v_mfma_f32_16x16x32_f16 v[172:175], v[196:199], v[14:17], v[26:29]
	v_mfma_f32_16x16x32_f16 v[176:179], v[192:195], v[6:9], v[22:25]
	v_mfma_f32_16x16x32_f16 v[180:183], v[192:195], v[14:17], v[26:29]
	v_mfma_f32_16x16x32_f16 v[168:171], v[188:191], v[2:5], v[168:171]
	v_mfma_f32_16x16x32_f16 v[172:175], v[188:191], v[18:21], v[172:175]
	v_mfma_f32_16x16x32_f16 v[176:179], v[184:187], v[2:5], v[176:179]
	v_mfma_f32_16x16x32_f16 v[180:183], v[184:187], v[18:21], v[180:183]
	ds_read_b128 v[184:187], v150 offset:30720
	ds_read_b128 v[188:191], v150 offset:28672
	ds_read_b128 v[192:195], v149 offset:30720
	ds_read_b128 v[196:199], v149 offset:28672
	s_nop 0
	v_exp_f32_e32 v39, v168
	s_nop 0
	v_exp_f32_e32 v43, v176
	v_exp_f32_e32 v80, v169
	v_exp_f32_e32 v155, v177
	v_exp_f32_e32 v169, v170
	v_exp_f32_e32 v170, v171
	v_exp_f32_e32 v76, v172
	v_exp_f32_e32 v77, v180
	v_exp_f32_e32 v172, v173
	v_exp_f32_e32 v176, v181
	v_exp_f32_e32 v173, v178
	v_exp_f32_e32 v174, v174
	v_exp_f32_e32 v177, v182
	v_exp_f32_e32 v171, v179
	v_cvt_pk_f16_f32 v168, v39, v80
	v_cvt_pk_f16_f32 v169, v169, v170
	v_cvt_pk_f16_f32 v170, v43, v155
	v_exp_f32_e32 v39, v175
	v_exp_f32_e32 v43, v183
	v_cvt_pk_f16_f32 v171, v173, v171
	v_cvt_pk_f16_f32 v172, v76, v172
	v_cvt_pk_f16_f32 v173, v174, v39
	v_cvt_pk_f16_f32 v174, v77, v176
	v_cvt_pk_f16_f32 v175, v177, v43
	s_waitcnt lgkmcnt(10)
	v_mfma_f32_16x16x32_f16 v[48:51], v[112:115], v[168:171], v[48:51]
	v_mfma_f32_16x16x32_f16 v[56:59], v[112:115], v[172:175], v[56:59]
	s_waitcnt lgkmcnt(8)
	v_mfma_f32_16x16x32_f16 v[72:75], v[116:119], v[168:171], v[72:75]
	v_mfma_f32_16x16x32_f16 v[60:63], v[116:119], v[172:175], v[60:63]
	s_waitcnt lgkmcnt(6)
	v_mfma_f32_16x16x32_f16 v[108:111], v[160:163], v[168:171], v[108:111]
	v_mfma_f32_16x16x32_f16 v[64:67], v[160:163], v[172:175], v[64:67]
	s_waitcnt lgkmcnt(4)
	v_mfma_f32_16x16x32_f16 v[52:55], v[164:167], v[168:171], v[52:55]
	v_mfma_f32_16x16x32_f16 v[68:71], v[164:167], v[172:175], v[68:71]
	ds_read_b64_tr_b16 v[112:113], v38 offset:61440
	ds_read_b64_tr_b16 v[114:115], v38 offset:63488
	ds_read_b64_tr_b16 v[116:117], v151 offset:61440
	ds_read_b64_tr_b16 v[118:119], v151 offset:63488
	ds_read_b64_tr_b16 v[160:161], v152 offset:61440
	ds_read_b64_tr_b16 v[162:163], v152 offset:63488
	ds_read_b64_tr_b16 v[164:165], v153 offset:61440
	ds_read_b64_tr_b16 v[166:167], v153 offset:63488
	v_mfma_f32_16x16x32_f16 v[156:159], v[10:13], v[168:171], v[156:159]
	v_mfma_f32_16x16x32_f16 v[44:47], v[10:13], v[172:175], v[44:47]
	s_waitcnt lgkmcnt(8)
	v_mfma_f32_16x16x32_f16 v[168:171], v[196:199], v[6:9], v[22:25]
	v_mfma_f32_16x16x32_f16 v[172:175], v[196:199], v[14:17], v[26:29]
	v_mfma_f32_16x16x32_f16 v[6:9], v[192:195], v[6:9], v[22:25]
	v_mfma_f32_16x16x32_f16 v[14:17], v[192:195], v[14:17], v[26:29]
	v_mfma_f32_16x16x32_f16 v[22:25], v[188:191], v[2:5], v[168:171]
	v_mfma_f32_16x16x32_f16 v[26:29], v[188:191], v[18:21], v[172:175]
	v_mfma_f32_16x16x32_f16 v[2:5], v[184:187], v[2:5], v[6:9]
	v_mfma_f32_16x16x32_f16 v[6:9], v[184:187], v[18:21], v[14:17]
	s_nop 7
	v_exp_f32_e32 v21, v7
	v_exp_f32_e32 v7, v4
	v_exp_f32_e32 v5, v5
	v_exp_f32_e32 v14, v22
	v_exp_f32_e32 v15, v2
	v_exp_f32_e32 v20, v6
	v_exp_f32_e32 v2, v23
	v_exp_f32_e32 v6, v3
	v_exp_f32_e32 v3, v24
	v_exp_f32_e32 v4, v25
	v_exp_f32_e32 v18, v26
	v_exp_f32_e32 v19, v27
	v_exp_f32_e32 v22, v28
	v_exp_f32_e32 v23, v8
	v_cvt_pk_f16_f32 v5, v7, v5
	v_exp_f32_e32 v7, v29
	v_exp_f32_e32 v9, v9
	v_cvt_pk_f16_f32 v2, v14, v2
	v_cvt_pk_f16_f32 v3, v3, v4
	v_cvt_pk_f16_f32 v4, v15, v6
	v_cvt_pk_f16_f32 v6, v18, v19
	v_cvt_pk_f16_f32 v7, v22, v7
	v_mfma_f32_16x16x32_f16 v[14:17], v[10:13], v[2:5], v[156:159]
	v_cvt_pk_f16_f32 v8, v20, v21
	v_cvt_pk_f16_f32 v9, v23, v9
	s_add_u32 s4, s21, s14
	s_waitcnt lgkmcnt(6)
; __device__ __forceinline__ unsigned pkh(float lo, float hi) { f32x2 v = {lo, hi}; h16x2 h = __builtin_convertvector(v, h16x2); return __builtin_bit_cast(unsigned, h); }
; __device__ __forceinline__ int pair16_dim(int G, int dt0) { return (G & 1) ? 16 * (dt0 + 1) + 4 * (G - 1) : 16 * dt0 + 4 * G; }
; __device__ __forceinline__ void store_o16(f16_t* rowp, const f32x4 (&o)[4], float il, int G) {
; #pragma unroll
;     for (int pr = 0; pr < 2; ++pr) { const int dt0 = 2 * pr;
;         u32x2 a, b; a.x = pkh(o[dt0][0] * il, o[dt0][1] * il); a.y = pkh(o[dt0][2] * il, o[dt0][3] * il); b.x = pkh(o[dt0 + 1][0] * il, o[dt0 + 1][1] * il); b.y = pkh(o[dt0 + 1][2] * il, o[dt0 + 1][3] * il);
;         *(u32x4*)(rowp + pair16_dim(G, dt0)) = pair16(a, b); }
; }
; template <bool Y8>
; __device__ __forceinline__ void xattn_chunk(const Frame& F, const Args& a, int chunk, const f16_t* P, int ldp, int qcol0, const float* gqm, f16_t* Y) {
;     ...
;         attn_tile2<false, true>(img, img + 32768, img, img + 32768, NMEM / 32, qa0, qa1, mba, 0, qb0, qb1, mbb, 0, oa, ob, lsa, lsb, lane);
;         const float ila = 1.0f / lsa, ilb = 1.0f / lsb;
;         if constexpr (Y8) { unsigned char* yp = (unsigned char*)Y + MIXW + head * HD; store_o8(yp + (size_t)rowa * DM, oa, ila, G); store_o8(yp + (size_t)rowb * DM, ob, ilb, G); }
;         else { f16_t* yp = Y + MIXW + head * HD; store_o16(yp + (size_t)rowa * DM, oa, ila, G); store_o16(yp + (size_t)rowb * DM, ob, ilb, G); }
;         __syncthreads();
;     }
	v_mfma_f32_16x16x32_f16 v[16:19], v[112:115], v[2:5], v[48:51]
	s_addc_u32 s5, s22, 0
	v_lshl_add_u64 v[28:29], s[4:5], 0, v[34:35]
	v_lshl_add_u64 v[38:39], s[4:5], 0, v[36:37]
	v_mfma_f32_16x16x32_f16 v[20:23], v[112:115], v[6:9], v[56:59]
	v_lshlrev_b32_e32 v80, 1, v82
	s_and_b64 s[2:3], exec, s[18:19]
	s_mov_b32 s14, 1
	s_waitcnt lgkmcnt(4)
	v_mfma_f32_16x16x32_f16 v[24:27], v[116:119], v[2:5], v[72:75]
	s_mov_b64 s[18:19], 0
	v_lshl_add_u64 v[28:29], v[28:29], 0, v[80:81]
	v_lshl_add_u64 v[38:39], v[38:39], 0, v[80:81]
	v_mfma_f32_16x16x32_f16 v[48:51], v[116:119], v[6:9], v[60:63]
	s_waitcnt lgkmcnt(2)
	v_mfma_f32_16x16x32_f16 v[56:59], v[160:163], v[2:5], v[108:111]
	v_mfma_f32_16x16x32_f16 v[60:63], v[160:163], v[6:9], v[64:67]
	s_waitcnt lgkmcnt(0)
	v_mfma_f32_16x16x32_f16 v[2:5], v[164:167], v[2:5], v[52:55]
	v_mfma_f32_16x16x32_f16 v[52:55], v[164:167], v[6:9], v[68:71]
	v_mfma_f32_16x16x32_f16 v[6:9], v[10:13], v[6:9], v[44:47]
	s_nop 7
	v_div_scale_f32 v7, s[4:5], v14, v14, 1.0
	v_div_scale_f32 v9, s[4:5], v6, v6, 1.0
	v_rcp_f32_e32 v11, v7
	v_rcp_f32_e32 v12, v9
	v_div_scale_f32 v8, vcc, 1.0, v14, 1.0
	v_fma_f32 v13, -v7, v11, 1.0
	v_fma_f32 v15, -v9, v12, 1.0
	v_fmac_f32_e32 v11, v13, v11
	v_div_scale_f32 v10, s[4:5], 1.0, v6, 1.0
	v_fmac_f32_e32 v12, v15, v12
	v_mul_f32_e32 v13, v8, v11
	v_mul_f32_e32 v15, v10, v12
	v_fma_f32 v43, -v7, v13, v8
	v_fma_f32 v44, -v9, v15, v10
	v_fmac_f32_e32 v13, v43, v11
	v_fmac_f32_e32 v15, v44, v12
	v_fma_f32 v7, -v7, v13, v8
	v_fma_f32 v9, -v9, v15, v10
	v_div_fmas_f32 v7, v7, v11, v13
	s_mov_b64 vcc, s[4:5]
	v_div_fixup_f32 v8, v7, v14, 1.0
	v_div_fmas_f32 v7, v9, v12, v15
	v_div_fixup_f32 v10, v7, v6, 1.0
	v_pk_mul_f32 v[6:7], v[8:9], v[16:17] op_sel_hi:[0,1]
	v_pk_mul_f32 v[12:13], v[8:9], v[18:19] op_sel_hi:[0,1]
	v_pk_mul_f32 v[14:15], v[8:9], v[24:25] op_sel_hi:[0,1]
	v_pk_mul_f32 v[16:17], v[8:9], v[26:27] op_sel_hi:[0,1]
	v_pk_mul_f32 v[18:19], v[8:9], v[56:57] op_sel_hi:[0,1]
	v_pk_mul_f32 v[24:25], v[8:9], v[58:59] op_sel_hi:[0,1]
	v_pk_mul_f32 v[26:27], v[8:9], v[2:3] op_sel_hi:[0,1]
	v_pk_mul_f32 v[44:45], v[8:9], v[4:5] op_sel_hi:[0,1]
	v_cvt_pk_f16_f32 v2, v6, v7
	v_cvt_pk_f16_f32 v3, v12, v13
	v_cvt_pk_f16_f32 v4, v14, v15
	v_cvt_pk_f16_f32 v5, v16, v17
	v_cvt_pk_f16_f32 v6, v18, v19
	v_pk_mul_f32 v[12:13], v[20:21], v[10:11] op_sel_hi:[1,0]
	v_pk_mul_f32 v[14:15], v[22:23], v[10:11] op_sel_hi:[1,0]
	v_pk_mul_f32 v[16:17], v[48:49], v[10:11] op_sel_hi:[1,0]
	v_pk_mul_f32 v[18:19], v[50:51], v[10:11] op_sel_hi:[1,0]
	v_cvt_pk_f16_f32 v7, v24, v25
	v_cvt_pk_f16_f32 v8, v26, v27
	v_pk_mul_f32 v[20:21], v[60:61], v[10:11] op_sel_hi:[1,0]
	v_pk_mul_f32 v[22:23], v[62:63], v[10:11] op_sel_hi:[1,0]
	v_pk_mul_f32 v[24:25], v[52:53], v[10:11] op_sel_hi:[1,0]
	v_pk_mul_f32 v[26:27], v[54:55], v[10:11] op_sel_hi:[1,0]
	v_cvt_pk_f16_f32 v10, v12, v13
	v_cvt_pk_f16_f32 v11, v14, v15
	v_cvt_pk_f16_f32 v12, v16, v17
	v_cvt_pk_f16_f32 v13, v18, v19
	v_cvt_pk_f16_f32 v9, v44, v45
	v_permlane16_swap_b32_e32 v2, v4
	v_permlane16_swap_b32_e32 v3, v5
	v_cvt_pk_f16_f32 v14, v20, v21
	v_cvt_pk_f16_f32 v15, v22, v23
	v_cvt_pk_f16_f32 v16, v24, v25
	v_cvt_pk_f16_f32 v17, v26, v27
	v_permlane16_swap_b32_e32 v10, v12
	v_permlane16_swap_b32_e32 v11, v13
	s_mov_b64 vcc, s[2:3]
	v_permlane16_swap_b32_e32 v6, v8
	v_permlane16_swap_b32_e32 v7, v9
	global_store_dwordx4 v[28:29], v[2:5], off
	global_store_dwordx4 v[28:29], v[6:9], off offset:64
	v_permlane16_swap_b32_e32 v14, v16
	v_permlane16_swap_b32_e32 v15, v17
	global_store_dwordx4 v[38:39], v[10:13], off
	global_store_dwordx4 v[38:39], v[14:17], off offset:64
	s_barrier
	s_cbranch_vccnz .LBB0_334
	s_cmp_eq_u32 s99, 1
	s_cbranch_scc0 .Lp2_latch
	s_mov_b32 s99, 2
	s_branch .Lp2_sgu
.Lp2_latch:
	s_add_i32 s42, s42, s88
	s_cmpk_gt_i32 s42, 0xff
	s_cbranch_scc0 .LBB0_323
